# GEMM K-loops: LDS-fragment wait moved ahead of the pre-MFMA barrier so the first MFMA issues right after release
# speedup vs baseline: 1.0030x; 1.0030x over previous
.LBB0_70:
	s_add_i32 s35, s18, 2
	s_add_u32 s16, s12, 0x100
	s_addc_u32 s17, s13, 0
	s_cmp_lg_u32 s34, s18
	s_cselect_b32 s22, s16, 0
	s_cselect_b32 s23, s17, 0
	s_add_u32 s18, s10, s22
	s_addc_u32 s19, s11, s23
	s_add_i32 s36, 0, 0x10000
	s_add_u32 s22, s8, s22
	s_addc_u32 s23, s9, s23
	v_lshl_add_u64 v[190:191], v[130:131], 0, s[12:13]
	s_add_i32 m0, s3, 0xc000
	ds_read_b128 v[170:173], v153
	ds_read_b128 v[178:181], v153 offset:2048
	ds_read_b128 v[186:189], v153 offset:4096
	ds_read_b128 v[220:223], v153 offset:6144
	ds_read_b128 v[174:177], v153 offset:1024
	ds_read_b128 v[182:185], v153 offset:3072
	ds_read_b128 v[216:219], v153 offset:5120
	ds_read_b128 v[224:227], v153 offset:7168
	global_load_lds_dwordx4 v[190:191], off
	v_lshl_add_u64 v[190:191], v[150:151], 0, s[12:13]
	s_add_i32 m0, s3, 0xe000
	s_nop 0
	global_load_lds_dwordx4 v[190:191], off
	s_waitcnt lgkmcnt(8)
	s_waitcnt vmcnt(10)
	s_waitcnt lgkmcnt(4)
	s_barrier
	v_mfma_f32_16x16x32_bf16 v[124:127], v[154:157], v[170:173], v[124:127]
	v_mfma_f32_16x16x32_bf16 v[120:123], v[162:165], v[170:173], v[120:123]
	v_mfma_f32_16x16x32_bf16 v[116:119], v[154:157], v[178:181], v[116:119]
	v_mfma_f32_16x16x32_bf16 v[108:111], v[162:165], v[178:181], v[108:111]
	v_mfma_f32_16x16x32_bf16 v[100:103], v[154:157], v[186:189], v[100:103]
	v_mfma_f32_16x16x32_bf16 v[92:95], v[162:165], v[186:189], v[92:95]
	v_mfma_f32_16x16x32_bf16 v[84:87], v[154:157], v[220:223], v[84:87]
	v_mfma_f32_16x16x32_bf16 v[76:79], v[162:165], v[220:223], v[76:79]
	s_waitcnt lgkmcnt(0)
	v_mfma_f32_16x16x32_bf16 v[124:127], v[158:161], v[174:177], v[124:127]
	v_mfma_f32_16x16x32_bf16 v[120:123], v[166:169], v[174:177], v[120:123]
	v_mfma_f32_16x16x32_bf16 v[116:119], v[158:161], v[182:185], v[116:119]
	v_mfma_f32_16x16x32_bf16 v[108:111], v[166:169], v[182:185], v[108:111]
	v_mfma_f32_16x16x32_bf16 v[100:103], v[158:161], v[216:219], v[100:103]
	v_mfma_f32_16x16x32_bf16 v[92:95], v[166:169], v[216:219], v[92:95]
	v_mfma_f32_16x16x32_bf16 v[84:87], v[158:161], v[224:227], v[84:87]
	v_mfma_f32_16x16x32_bf16 v[76:79], v[166:169], v[224:227], v[76:79]
	s_barrier
	s_add_i32 s37, 0, 0x14000
	v_add_u32_e32 v190, s37, v152
	s_add_i32 s12, s36, s26
	ds_read_b128 v[228:231], v190
	ds_read_b128 v[236:239], v190 offset:2048
	ds_read_b128 v[232:235], v190 offset:1024
	ds_read_b128 v[240:243], v190 offset:3072
	v_lshl_add_u64 v[190:191], s[22:23], 0, v[132:133]
	s_mov_b32 m0, s12
	v_lshl_add_u64 v[244:245], s[22:23], 0, v[128:129]
	global_load_lds_dwordx4 v132, s[22:23]
	s_add_i32 m0, s12, 0x2000
	s_nop 0
	global_load_lds_dwordx4 v128, s[22:23]
	s_waitcnt vmcnt(10)
	s_waitcnt lgkmcnt(2)
	s_barrier
	v_mfma_f32_16x16x32_bf16 v[112:115], v[228:231], v[170:173], v[112:115]
	v_mfma_f32_16x16x32_bf16 v[104:107], v[236:239], v[170:173], v[104:107]
	v_mfma_f32_16x16x32_bf16 v[96:99], v[228:231], v[178:181], v[96:99]
	v_mfma_f32_16x16x32_bf16 v[88:91], v[236:239], v[178:181], v[88:91]
	v_mfma_f32_16x16x32_bf16 v[80:83], v[228:231], v[186:189], v[80:83]
	v_mfma_f32_16x16x32_bf16 v[72:75], v[236:239], v[186:189], v[72:75]
	v_mfma_f32_16x16x32_bf16 v[68:71], v[228:231], v[220:223], v[68:71]
	v_mfma_f32_16x16x32_bf16 v[64:67], v[236:239], v[220:223], v[64:67]
	s_waitcnt lgkmcnt(0)
	v_mfma_f32_16x16x32_bf16 v[112:115], v[232:235], v[174:177], v[112:115]
	v_mfma_f32_16x16x32_bf16 v[104:107], v[240:243], v[174:177], v[104:107]
	v_mfma_f32_16x16x32_bf16 v[96:99], v[232:235], v[182:185], v[96:99]
	v_mfma_f32_16x16x32_bf16 v[88:91], v[240:243], v[182:185], v[88:91]
	v_mfma_f32_16x16x32_bf16 v[80:83], v[232:235], v[216:219], v[80:83]
	v_mfma_f32_16x16x32_bf16 v[72:75], v[240:243], v[216:219], v[72:75]
	v_mfma_f32_16x16x32_bf16 v[68:71], v[232:235], v[224:227], v[68:71]
	v_mfma_f32_16x16x32_bf16 v[64:67], v[240:243], v[224:227], v[64:67]
	s_mov_b32 m0, s3
	s_barrier
	ds_read_b128 v[170:173], v153 offset:16384
	ds_read_b128 v[178:181], v153 offset:18432
	ds_read_b128 v[186:189], v153 offset:20480
	ds_read_b128 v[220:223], v153 offset:22528
	ds_read_b128 v[174:177], v153 offset:17408
	ds_read_b128 v[182:185], v153 offset:19456
	ds_read_b128 v[216:219], v153 offset:21504
	ds_read_b128 v[224:227], v153 offset:23552
	global_load_lds_dwordx4 v132, s[18:19]
	s_mov_b32 m0, s5
	s_nop 0
	global_load_lds_dwordx4 v128, s[18:19]
	s_waitcnt vmcnt(10)
	s_waitcnt lgkmcnt(4)
	s_barrier
	v_mfma_f32_16x16x32_bf16 v[60:63], v[154:157], v[170:173], v[60:63]
	v_mfma_f32_16x16x32_bf16 v[56:59], v[162:165], v[170:173], v[56:59]
	v_mfma_f32_16x16x32_bf16 v[52:55], v[154:157], v[178:181], v[52:55]
	v_mfma_f32_16x16x32_bf16 v[44:47], v[162:165], v[178:181], v[44:47]
	v_mfma_f32_16x16x32_bf16 v[36:39], v[154:157], v[186:189], v[36:39]
	v_mfma_f32_16x16x32_bf16 v[28:31], v[162:165], v[186:189], v[28:31]
	v_mfma_f32_16x16x32_bf16 v[20:23], v[154:157], v[220:223], v[20:23]
	v_mfma_f32_16x16x32_bf16 v[12:15], v[162:165], v[220:223], v[12:15]
	s_waitcnt lgkmcnt(0)
	v_mfma_f32_16x16x32_bf16 v[60:63], v[158:161], v[174:177], v[60:63]
	v_mfma_f32_16x16x32_bf16 v[56:59], v[166:169], v[174:177], v[56:59]
	v_mfma_f32_16x16x32_bf16 v[52:55], v[158:161], v[182:185], v[52:55]
	v_mfma_f32_16x16x32_bf16 v[44:47], v[166:169], v[182:185], v[44:47]
	v_mfma_f32_16x16x32_bf16 v[36:39], v[158:161], v[216:219], v[36:39]
	v_mfma_f32_16x16x32_bf16 v[28:31], v[166:169], v[216:219], v[28:31]
	v_mfma_f32_16x16x32_bf16 v[20:23], v[158:161], v[224:227], v[20:23]
	v_mfma_f32_16x16x32_bf16 v[12:15], v[166:169], v[224:227], v[12:15]
	s_barrier
	s_add_u32 s12, s22, s25
	s_addc_u32 s13, s23, 0
	s_add_i32 s22, s37, s26
	v_lshl_add_u64 v[250:251], s[12:13], 0, v[132:133]
	s_mov_b32 m0, s22
	v_lshl_add_u64 v[252:253], s[12:13], 0, v[128:129]
	global_load_lds_dwordx4 v132, s[12:13]
	s_add_i32 m0, s22, 0x2000
	s_nop 0
	global_load_lds_dwordx4 v128, s[12:13]
	v_add_u32_e32 v166, 0x18000, v152
	ds_read_b128 v[154:157], v166
	ds_read_b128 v[158:161], v166 offset:1024
	ds_read_b128 v[162:165], v166 offset:2048
	ds_read_b128 v[166:169], v166 offset:3072
	s_waitcnt vmcnt(10)
	s_barrier
	v_mfma_f32_16x16x32_bf16 v[48:51], v[228:231], v[170:173], v[48:51]
	v_mfma_f32_16x16x32_bf16 v[40:43], v[236:239], v[170:173], v[40:43]
	v_mfma_f32_16x16x32_bf16 v[32:35], v[228:231], v[178:181], v[32:35]
	v_mfma_f32_16x16x32_bf16 v[24:27], v[236:239], v[178:181], v[24:27]
	v_mfma_f32_16x16x32_bf16 v[16:19], v[228:231], v[186:189], v[16:19]
	v_mfma_f32_16x16x32_bf16 v[8:11], v[236:239], v[186:189], v[8:11]
	v_mfma_f32_16x16x32_bf16 v[4:7], v[228:231], v[220:223], v[4:7]
	v_mfma_f32_16x16x32_bf16 v[0:3], v[236:239], v[220:223], v[0:3]
	v_mfma_f32_16x16x32_bf16 v[48:51], v[232:235], v[174:177], v[48:51]
	v_mfma_f32_16x16x32_bf16 v[40:43], v[240:243], v[174:177], v[40:43]
	v_mfma_f32_16x16x32_bf16 v[32:35], v[232:235], v[182:185], v[32:35]
	v_mfma_f32_16x16x32_bf16 v[24:27], v[240:243], v[182:185], v[24:27]
	v_mfma_f32_16x16x32_bf16 v[16:19], v[232:235], v[216:219], v[16:19]
	v_mfma_f32_16x16x32_bf16 v[8:11], v[240:243], v[216:219], v[8:11]
	v_mfma_f32_16x16x32_bf16 v[4:7], v[232:235], v[224:227], v[4:7]
	v_mfma_f32_16x16x32_bf16 v[0:3], v[240:243], v[224:227], v[0:3]
	s_add_i32 s22, 0, 0x18000
	s_barrier
	s_add_u32 s12, s18, s25
	s_addc_u32 s13, s19, 0
	s_mov_b32 m0, s27
	ds_read_b128 v[170:173], v153 offset:32768
	ds_read_b128 v[178:181], v153 offset:34816
	ds_read_b128 v[186:189], v153 offset:36864
	ds_read_b128 v[220:223], v153 offset:38912
	ds_read_b128 v[174:177], v153 offset:33792
	ds_read_b128 v[182:185], v153 offset:35840
	ds_read_b128 v[216:219], v153 offset:37888
	ds_read_b128 v[224:227], v153 offset:39936
	global_load_lds_dwordx4 v132, s[12:13]
	s_mov_b32 m0, s28
	s_nop 0
	global_load_lds_dwordx4 v128, s[12:13]
	s_waitcnt lgkmcnt(8)
	s_waitcnt vmcnt(10)
	s_waitcnt lgkmcnt(4)
	s_barrier
	v_mfma_f32_16x16x32_bf16 v[124:127], v[154:157], v[170:173], v[124:127]
	v_mfma_f32_16x16x32_bf16 v[120:123], v[162:165], v[170:173], v[120:123]
	v_mfma_f32_16x16x32_bf16 v[116:119], v[154:157], v[178:181], v[116:119]
	v_mfma_f32_16x16x32_bf16 v[108:111], v[162:165], v[178:181], v[108:111]
	v_mfma_f32_16x16x32_bf16 v[100:103], v[154:157], v[186:189], v[100:103]
	v_mfma_f32_16x16x32_bf16 v[92:95], v[162:165], v[186:189], v[92:95]
	v_mfma_f32_16x16x32_bf16 v[84:87], v[154:157], v[220:223], v[84:87]
	v_mfma_f32_16x16x32_bf16 v[76:79], v[162:165], v[220:223], v[76:79]
	s_waitcnt lgkmcnt(0)
	v_mfma_f32_16x16x32_bf16 v[124:127], v[158:161], v[174:177], v[124:127]
	v_mfma_f32_16x16x32_bf16 v[120:123], v[166:169], v[174:177], v[120:123]
	v_mfma_f32_16x16x32_bf16 v[116:119], v[158:161], v[182:185], v[116:119]
	v_mfma_f32_16x16x32_bf16 v[108:111], v[166:169], v[182:185], v[108:111]
	v_mfma_f32_16x16x32_bf16 v[100:103], v[158:161], v[216:219], v[100:103]
	v_mfma_f32_16x16x32_bf16 v[92:95], v[166:169], v[216:219], v[92:95]
	v_mfma_f32_16x16x32_bf16 v[84:87], v[158:161], v[224:227], v[84:87]
	v_mfma_f32_16x16x32_bf16 v[76:79], v[166:169], v[224:227], v[76:79]
	s_barrier
	s_add_i32 s12, 0, 0x1c000
	s_add_i32 s13, s22, s26
	v_add_u32_e32 v200, s12, v152
	v_lshl_add_u64 v[190:191], v[190:191], 0, s[66:67]
	s_mov_b32 m0, s13
	ds_read_b128 v[228:231], v200
	ds_read_b128 v[236:239], v200 offset:2048
	ds_read_b128 v[232:235], v200 offset:1024
	ds_read_b128 v[240:243], v200 offset:3072
	global_load_lds_dwordx4 v[190:191], off
	v_lshl_add_u64 v[190:191], v[244:245], 0, s[66:67]
	s_add_i32 m0, s13, 0x2000
	s_nop 0
	global_load_lds_dwordx4 v[190:191], off
	s_waitcnt vmcnt(10)
	s_waitcnt lgkmcnt(2)
	s_barrier
	v_mfma_f32_16x16x32_bf16 v[112:115], v[228:231], v[170:173], v[112:115]
	v_mfma_f32_16x16x32_bf16 v[104:107], v[236:239], v[170:173], v[104:107]
	v_mfma_f32_16x16x32_bf16 v[96:99], v[228:231], v[178:181], v[96:99]
	v_mfma_f32_16x16x32_bf16 v[88:91], v[236:239], v[178:181], v[88:91]
	v_mfma_f32_16x16x32_bf16 v[80:83], v[228:231], v[186:189], v[80:83]
	v_mfma_f32_16x16x32_bf16 v[72:75], v[236:239], v[186:189], v[72:75]
	v_mfma_f32_16x16x32_bf16 v[68:71], v[228:231], v[220:223], v[68:71]
	v_mfma_f32_16x16x32_bf16 v[64:67], v[236:239], v[220:223], v[64:67]
	s_waitcnt lgkmcnt(0)
	v_mfma_f32_16x16x32_bf16 v[112:115], v[232:235], v[174:177], v[112:115]
	v_mfma_f32_16x16x32_bf16 v[104:107], v[240:243], v[174:177], v[104:107]
	v_mfma_f32_16x16x32_bf16 v[96:99], v[232:235], v[182:185], v[96:99]
	v_mfma_f32_16x16x32_bf16 v[88:91], v[240:243], v[182:185], v[88:91]
	v_mfma_f32_16x16x32_bf16 v[80:83], v[232:235], v[216:219], v[80:83]
	v_mfma_f32_16x16x32_bf16 v[72:75], v[240:243], v[216:219], v[72:75]
	v_mfma_f32_16x16x32_bf16 v[68:71], v[232:235], v[224:227], v[68:71]
	v_mfma_f32_16x16x32_bf16 v[64:67], v[240:243], v[224:227], v[64:67]
	s_mov_b32 m0, s30
	s_barrier
	ds_read_b128 v[170:173], v153 offset:49152
	ds_read_b128 v[178:181], v153 offset:51200
	ds_read_b128 v[186:189], v153 offset:53248
	ds_read_b128 v[220:223], v153 offset:55296
	ds_read_b128 v[174:177], v153 offset:50176
	ds_read_b128 v[182:185], v153 offset:52224
	ds_read_b128 v[216:219], v153 offset:54272
	ds_read_b128 v[224:227], v153 offset:56320
	s_add_u32 s98, s18, 0x80
	s_addc_u32 s99, s19, 0
	global_load_lds_dwordx4 v132, s[98:99]
	s_mov_b32 m0, s31
	s_nop 0
	global_load_lds_dwordx4 v128, s[98:99]
	s_waitcnt vmcnt(10)
	s_waitcnt lgkmcnt(4)
	s_barrier
	v_mfma_f32_16x16x32_bf16 v[60:63], v[154:157], v[170:173], v[60:63]
	v_mfma_f32_16x16x32_bf16 v[56:59], v[162:165], v[170:173], v[56:59]
	v_mfma_f32_16x16x32_bf16 v[52:55], v[154:157], v[178:181], v[52:55]
	v_mfma_f32_16x16x32_bf16 v[44:47], v[162:165], v[178:181], v[44:47]
	v_mfma_f32_16x16x32_bf16 v[36:39], v[154:157], v[186:189], v[36:39]
	v_mfma_f32_16x16x32_bf16 v[28:31], v[162:165], v[186:189], v[28:31]
	v_mfma_f32_16x16x32_bf16 v[20:23], v[154:157], v[220:223], v[20:23]
	v_mfma_f32_16x16x32_bf16 v[12:15], v[162:165], v[220:223], v[12:15]
	s_waitcnt lgkmcnt(0)
	v_mfma_f32_16x16x32_bf16 v[60:63], v[158:161], v[174:177], v[60:63]
	v_mfma_f32_16x16x32_bf16 v[56:59], v[166:169], v[174:177], v[56:59]
	v_mfma_f32_16x16x32_bf16 v[52:55], v[158:161], v[182:185], v[52:55]
	v_mfma_f32_16x16x32_bf16 v[44:47], v[166:169], v[182:185], v[44:47]
	v_mfma_f32_16x16x32_bf16 v[36:39], v[158:161], v[216:219], v[36:39]
	v_mfma_f32_16x16x32_bf16 v[28:31], v[166:169], v[216:219], v[28:31]
	v_mfma_f32_16x16x32_bf16 v[20:23], v[158:161], v[224:227], v[20:23]
	v_mfma_f32_16x16x32_bf16 v[12:15], v[166:169], v[224:227], v[12:15]
	s_barrier
	s_add_i32 s12, s12, s26
	v_lshl_add_u64 v[154:155], v[250:251], 0, s[66:67]
	s_mov_b32 m0, s12
	s_nop 0
	global_load_lds_dwordx4 v[154:155], off
	v_lshl_add_u64 v[154:155], v[252:253], 0, s[66:67]
	s_add_i32 m0, s12, 0x2000
	s_nop 0
	global_load_lds_dwordx4 v[154:155], off
	v_add_u32_e32 v166, 0x10000, v152
	ds_read_b128 v[154:157], v166
	ds_read_b128 v[158:161], v166 offset:1024
	ds_read_b128 v[162:165], v166 offset:2048
	ds_read_b128 v[166:169], v166 offset:3072
	s_waitcnt vmcnt(10)
	s_barrier
	v_mfma_f32_16x16x32_bf16 v[48:51], v[228:231], v[170:173], v[48:51]
	v_mfma_f32_16x16x32_bf16 v[40:43], v[236:239], v[170:173], v[40:43]
	v_mfma_f32_16x16x32_bf16 v[32:35], v[228:231], v[178:181], v[32:35]
	v_mfma_f32_16x16x32_bf16 v[24:27], v[236:239], v[178:181], v[24:27]
	v_mfma_f32_16x16x32_bf16 v[16:19], v[228:231], v[186:189], v[16:19]
	v_mfma_f32_16x16x32_bf16 v[8:11], v[236:239], v[186:189], v[8:11]
	v_mfma_f32_16x16x32_bf16 v[4:7], v[228:231], v[220:223], v[4:7]
	v_mfma_f32_16x16x32_bf16 v[0:3], v[236:239], v[220:223], v[0:3]
	v_mfma_f32_16x16x32_bf16 v[48:51], v[232:235], v[174:177], v[48:51]
	v_mfma_f32_16x16x32_bf16 v[40:43], v[240:243], v[174:177], v[40:43]
	v_mfma_f32_16x16x32_bf16 v[32:35], v[232:235], v[182:185], v[32:35]
	v_mfma_f32_16x16x32_bf16 v[24:27], v[240:243], v[182:185], v[24:27]
	v_mfma_f32_16x16x32_bf16 v[16:19], v[232:235], v[216:219], v[16:19]
	v_mfma_f32_16x16x32_bf16 v[8:11], v[240:243], v[216:219], v[8:11]
	v_mfma_f32_16x16x32_bf16 v[4:7], v[232:235], v[224:227], v[4:7]
	v_mfma_f32_16x16x32_bf16 v[0:3], v[240:243], v[224:227], v[0:3]
	s_cmp_ge_u32 s35, s29
	s_mov_b64 s[12:13], s[16:17]
	s_mov_b32 s18, s35
	s_barrier
	s_cbranch_scc0 .LBB0_70
	s_waitcnt lgkmcnt(0)
	s_and_b64 s[6:7], s[6:7], exec
	v_mov_b32_e32 v128, v135
	s_mov_b64 s[6:7], s[0:1]
	s_load_dwordx2 s[6:7], s[6:7], 0x88
	s_cselect_b32 s3, 0x2000, 0
	v_readfirstlane_b32 s5, v128
	v_lshrrev_b32_e32 v129, 2, v128
	v_cvt_pk_bf16_f32 v104, v104, v105
	s_waitcnt lgkmcnt(0)
	s_add_u32 s6, s6, 0xfea4400
	s_addc_u32 s7, s7, 0
	s_ashr_i32 s8, s5, 2
	s_andn2_b32 s8, s8, 63
	v_and_or_b32 v128, v128, 15, s8
	s_lshr_b32 s5, s5, 1
	v_lshl_add_u32 v150, s2, 8, v128
	s_lshl_b32 s2, s4, s15
	s_and_b32 s5, s5, 0x60
	s_add_i32 s2, s2, s3
	v_and_or_b32 v132, v129, 12, s5
	v_add_u32_e32 v130, s2, v150
	v_mov_b64_e32 v[128:129], s[6:7]
	v_mad_i64_i32 v[130:131], s[4:5], v130, s96, v[128:129]
	s_lshl_b32 s58, s58, 9
	v_lshl_add_u64 v[130:131], v[130:131], 0, s[58:59]
	v_lshlrev_b32_e32 v132, 1, v132
	v_lshl_add_u64 v[130:131], v[130:131], 0, v[132:133]
	v_cvt_pk_bf16_f32 v105, v106, v107
	global_store_dwordx2 v[130:131], v[104:105], off offset:1824
	v_add3_u32 v104, s2, 16, v150
	v_mad_i64_i32 v[104:105], s[4:5], v104, s96, v[128:129]
	v_lshl_add_u64 v[104:105], v[104:105], 0, s[58:59]
	v_lshl_add_u64 v[104:105], v[104:105], 0, v[132:133]
	v_cvt_pk_bf16_f32 v88, v88, v89
	v_cvt_pk_bf16_f32 v89, v90, v91
	global_store_dwordx2 v[104:105], v[88:89], off offset:1824
	v_add3_u32 v88, s2, 32, v150
	v_mad_i64_i32 v[88:89], s[4:5], v88, s96, v[128:129]
	v_lshl_add_u64 v[88:89], v[88:89], 0, s[58:59]
	v_lshl_add_u64 v[88:89], v[88:89], 0, v[132:133]
	v_cvt_pk_bf16_f32 v72, v72, v73
	v_cvt_pk_bf16_f32 v73, v74, v75
	global_store_dwordx2 v[88:89], v[72:73], off offset:1824
	v_add3_u32 v72, s2, 48, v150
	v_mad_i64_i32 v[72:73], s[4:5], v72, s96, v[128:129]
	v_lshl_add_u64 v[72:73], v[72:73], 0, s[58:59]
	v_lshl_add_u64 v[72:73], v[72:73], 0, v[132:133]
	v_cvt_pk_bf16_f32 v64, v64, v65
	s_add_i32 s3, s2, 0x80
	v_cvt_pk_bf16_f32 v65, v66, v67
	global_store_dwordx2 v[72:73], v[64:65], off offset:1824
	v_add_u32_e32 v64, s3, v150
	v_mad_i64_i32 v[64:65], s[4:5], v64, s96, v[128:129]
	v_lshl_add_u64 v[64:65], v[64:65], 0, s[58:59]
	v_lshl_add_u64 v[64:65], v[64:65], 0, v[132:133]
	v_cvt_pk_bf16_f32 v40, v40, v41
	s_add_i32 s3, s2, 0x90
	v_cvt_pk_bf16_f32 v41, v42, v43
	global_store_dwordx2 v[64:65], v[40:41], off offset:1824
	v_add_u32_e32 v40, s3, v150
	v_mad_i64_i32 v[40:41], s[4:5], v40, s96, v[128:129]
	v_lshl_add_u64 v[40:41], v[40:41], 0, s[58:59]
	v_lshl_add_u64 v[40:41], v[40:41], 0, v[132:133]
	v_cvt_pk_bf16_f32 v24, v24, v25
	s_add_i32 s3, s2, 0xa0
	v_cvt_pk_bf16_f32 v25, v26, v27
	global_store_dwordx2 v[40:41], v[24:25], off offset:1824
	v_add_u32_e32 v24, s3, v150
	v_mad_i64_i32 v[24:25], s[4:5], v24, s96, v[128:129]
	v_lshl_add_u64 v[24:25], v[24:25], 0, s[58:59]
	v_lshl_add_u64 v[24:25], v[24:25], 0, v[132:133]
	v_cvt_pk_bf16_f32 v8, v8, v9
	s_addk_i32 s2, 0xb0
	v_cvt_pk_bf16_f32 v9, v10, v11
	global_store_dwordx2 v[24:25], v[8:9], off offset:1824
	v_add_u32_e32 v8, s2, v150
	v_mad_i64_i32 v[8:9], s[2:3], v8, s96, v[128:129]
	v_lshl_add_u64 v[8:9], v[8:9], 0, s[58:59]
	v_cvt_pk_bf16_f32 v106, v116, v117
	v_cvt_pk_bf16_f32 v107, v118, v119
	v_cvt_pk_bf16_f32 v90, v100, v101
	v_cvt_pk_bf16_f32 v91, v102, v103
	v_cvt_pk_bf16_f32 v74, v84, v85
	v_cvt_pk_bf16_f32 v75, v86, v87
	v_cvt_pk_bf16_f32 v42, v52, v53
	v_cvt_pk_bf16_f32 v43, v54, v55
	v_cvt_pk_bf16_f32 v26, v36, v37
	v_cvt_pk_bf16_f32 v27, v38, v39
	v_lshl_add_u64 v[8:9], v[8:9], 0, v[132:133]
	v_cvt_pk_bf16_f32 v10, v20, v21
	v_cvt_pk_bf16_f32 v11, v22, v23
	v_cvt_pk_bf16_f32 v124, v124, v125
	v_cvt_pk_bf16_f32 v125, v126, v127
	global_store_dwordx2 v[130:131], v[124:125], off offset:1536
	v_cvt_pk_bf16_f32 v120, v120, v121
	v_cvt_pk_bf16_f32 v121, v122, v123
	global_store_dwordx2 v[130:131], v[120:121], off offset:1568
	v_cvt_pk_bf16_f32 v112, v112, v113
	v_cvt_pk_bf16_f32 v113, v114, v115
	global_store_dwordx2 v[130:131], v[112:113], off offset:1792
	global_store_dwordx2 v[104:105], v[106:107], off offset:1536
	v_cvt_pk_bf16_f32 v106, v108, v109
	v_cvt_pk_bf16_f32 v107, v110, v111
	global_store_dwordx2 v[104:105], v[106:107], off offset:1568
	v_cvt_pk_bf16_f32 v96, v96, v97
	v_cvt_pk_bf16_f32 v97, v98, v99
	global_store_dwordx2 v[104:105], v[96:97], off offset:1792
	global_store_dwordx2 v[88:89], v[90:91], off offset:1536
	v_cvt_pk_bf16_f32 v90, v92, v93
	v_cvt_pk_bf16_f32 v91, v94, v95
	global_store_dwordx2 v[88:89], v[90:91], off offset:1568
	v_cvt_pk_bf16_f32 v80, v80, v81
	v_cvt_pk_bf16_f32 v81, v82, v83
	global_store_dwordx2 v[88:89], v[80:81], off offset:1792
	global_store_dwordx2 v[72:73], v[74:75], off offset:1536
	v_cvt_pk_bf16_f32 v74, v76, v77
	v_cvt_pk_bf16_f32 v75, v78, v79
	global_store_dwordx2 v[72:73], v[74:75], off offset:1568
	v_cvt_pk_bf16_f32 v68, v68, v69
	v_cvt_pk_bf16_f32 v69, v70, v71
	global_store_dwordx2 v[72:73], v[68:69], off offset:1792
	v_cvt_pk_bf16_f32 v60, v60, v61
	v_cvt_pk_bf16_f32 v61, v62, v63
	global_store_dwordx2 v[64:65], v[60:61], off offset:1536
	v_cvt_pk_bf16_f32 v56, v56, v57
	v_cvt_pk_bf16_f32 v57, v58, v59
	global_store_dwordx2 v[64:65], v[56:57], off offset:1568
	v_cvt_pk_bf16_f32 v48, v48, v49
	v_cvt_pk_bf16_f32 v49, v50, v51
	global_store_dwordx2 v[64:65], v[48:49], off offset:1792
	global_store_dwordx2 v[40:41], v[42:43], off offset:1536
	v_cvt_pk_bf16_f32 v42, v44, v45
	v_cvt_pk_bf16_f32 v43, v46, v47
	global_store_dwordx2 v[40:41], v[42:43], off offset:1568
	v_cvt_pk_bf16_f32 v32, v32, v33
	v_cvt_pk_bf16_f32 v33, v34, v35
	global_store_dwordx2 v[40:41], v[32:33], off offset:1792
	global_store_dwordx2 v[24:25], v[26:27], off offset:1536
	v_cvt_pk_bf16_f32 v26, v28, v29
	v_cvt_pk_bf16_f32 v27, v30, v31
	global_store_dwordx2 v[24:25], v[26:27], off offset:1568
	v_cvt_pk_bf16_f32 v16, v16, v17
	v_cvt_pk_bf16_f32 v17, v18, v19
	global_store_dwordx2 v[24:25], v[16:17], off offset:1792
	global_store_dwordx2 v[8:9], v[10:11], off offset:1536
	v_cvt_pk_bf16_f32 v10, v12, v13
	v_cvt_pk_bf16_f32 v11, v14, v15
	global_store_dwordx2 v[8:9], v[10:11], off offset:1568
	v_cvt_pk_bf16_f32 v4, v4, v5
	v_cvt_pk_bf16_f32 v5, v6, v7
	global_store_dwordx2 v[8:9], v[4:5], off offset:1792
	v_cvt_pk_bf16_f32 v0, v0, v1
	v_cvt_pk_bf16_f32 v1, v2, v3
	global_store_dwordx2 v[8:9], v[0:1], off offset:1824
	s_waitcnt vmcnt(0)
	s_cmpk_lt_u32 s14, 0x100
	s_cbranch_scc0 .LBB0_73
	s_barrier

.LBB0_145:
	s_add_u32 s6, s2, 0xfffc0080
	s_addc_u32 s7, s3, -1
	s_add_i32 s29, 0, 0x10000
	s_cmp_eq_u32 s28, 12
	s_cselect_b32 s11, s9, s7
	s_cselect_b32 s10, s12, s6
	s_cselect_b32 s7, s13, s27
	s_cselect_b32 s6, s17, s19
	s_add_i32 m0, s50, 0xc000
	ds_read_b128 v[170:173], v216
	ds_read_b128 v[178:181], v216 offset:2048
	ds_read_b128 v[186:189], v216 offset:4096
	ds_read_b128 v[222:225], v216 offset:6144
	ds_read_b128 v[174:177], v216 offset:1024
	ds_read_b128 v[182:185], v216 offset:3072
	ds_read_b128 v[218:221], v216 offset:5120
	ds_read_b128 v[226:229], v216 offset:7168
	global_load_lds_dwordx4 v154, s[2:3]
	s_add_i32 m0, s50, 0xe000
	s_nop 0
	global_load_lds_dwordx4 v156, s[2:3]
	s_waitcnt lgkmcnt(8)
	s_waitcnt vmcnt(10)
	s_waitcnt lgkmcnt(4)
	s_barrier
	v_mfma_f32_16x16x32_bf16 v[124:127], v[128:131], v[170:173], v[124:127]
	v_mfma_f32_16x16x32_bf16 v[120:123], v[162:165], v[170:173], v[120:123]
	v_mfma_f32_16x16x32_bf16 v[108:111], v[128:131], v[178:181], v[108:111]
	v_mfma_f32_16x16x32_bf16 v[104:107], v[162:165], v[178:181], v[104:107]
	v_mfma_f32_16x16x32_bf16 v[92:95], v[128:131], v[186:189], v[92:95]
	v_mfma_f32_16x16x32_bf16 v[88:91], v[162:165], v[186:189], v[88:91]
	v_mfma_f32_16x16x32_bf16 v[76:79], v[128:131], v[222:225], v[76:79]
	v_mfma_f32_16x16x32_bf16 v[72:75], v[162:165], v[222:225], v[72:75]
	s_waitcnt lgkmcnt(0)
	v_mfma_f32_16x16x32_bf16 v[124:127], v[158:161], v[174:177], v[124:127]
	v_mfma_f32_16x16x32_bf16 v[120:123], v[166:169], v[174:177], v[120:123]
	v_mfma_f32_16x16x32_bf16 v[108:111], v[158:161], v[182:185], v[108:111]
	v_mfma_f32_16x16x32_bf16 v[104:107], v[166:169], v[182:185], v[104:107]
	v_mfma_f32_16x16x32_bf16 v[92:95], v[158:161], v[218:221], v[92:95]
	v_mfma_f32_16x16x32_bf16 v[88:91], v[166:169], v[218:221], v[88:91]
	v_mfma_f32_16x16x32_bf16 v[76:79], v[158:161], v[226:229], v[76:79]
	v_mfma_f32_16x16x32_bf16 v[72:75], v[166:169], v[226:229], v[72:75]
	s_barrier
	s_add_i32 s34, 0, 0x14000
	s_add_i32 s29, s29, s15
	v_add_u32_e32 v132, s34, v215
	s_mov_b32 m0, s29
	ds_read_b128 v[230:233], v132
	ds_read_b128 v[238:241], v132 offset:2048
	ds_read_b128 v[234:237], v132 offset:1024
	ds_read_b128 v[242:245], v132 offset:3072
	global_load_lds_dwordx4 v150, s[6:7]
	s_add_i32 m0, s29, 0x2000
	s_nop 0
	global_load_lds_dwordx4 v152, s[6:7]
	s_waitcnt vmcnt(10)
	s_waitcnt lgkmcnt(2)
	s_barrier
	v_mfma_f32_16x16x32_bf16 v[116:119], v[230:233], v[170:173], v[116:119]
	v_mfma_f32_16x16x32_bf16 v[112:115], v[238:241], v[170:173], v[112:115]
	v_mfma_f32_16x16x32_bf16 v[100:103], v[230:233], v[178:181], v[100:103]
	v_mfma_f32_16x16x32_bf16 v[96:99], v[238:241], v[178:181], v[96:99]
	v_mfma_f32_16x16x32_bf16 v[84:87], v[230:233], v[186:189], v[84:87]
	v_mfma_f32_16x16x32_bf16 v[80:83], v[238:241], v[186:189], v[80:83]
	v_mfma_f32_16x16x32_bf16 v[68:71], v[230:233], v[222:225], v[68:71]
	v_mfma_f32_16x16x32_bf16 v[64:67], v[238:241], v[222:225], v[64:67]
	s_waitcnt lgkmcnt(0)
	v_mfma_f32_16x16x32_bf16 v[116:119], v[234:237], v[174:177], v[116:119]
	v_mfma_f32_16x16x32_bf16 v[112:115], v[242:245], v[174:177], v[112:115]
	v_mfma_f32_16x16x32_bf16 v[100:103], v[234:237], v[182:185], v[100:103]
	v_mfma_f32_16x16x32_bf16 v[96:99], v[242:245], v[182:185], v[96:99]
	v_mfma_f32_16x16x32_bf16 v[84:87], v[234:237], v[218:221], v[84:87]
	v_mfma_f32_16x16x32_bf16 v[80:83], v[242:245], v[218:221], v[80:83]
	v_mfma_f32_16x16x32_bf16 v[68:71], v[234:237], v[226:229], v[68:71]
	v_mfma_f32_16x16x32_bf16 v[64:67], v[242:245], v[226:229], v[64:67]
	s_mov_b32 m0, s50
	v_lshl_add_u64 v[248:249], s[10:11], 0, v[150:151]
	s_barrier
	ds_read_b128 v[170:173], v216 offset:16384
	ds_read_b128 v[178:181], v216 offset:18432
	ds_read_b128 v[186:189], v216 offset:20480
	ds_read_b128 v[222:225], v216 offset:22528
	ds_read_b128 v[174:177], v216 offset:17408
	ds_read_b128 v[182:185], v216 offset:19456
	ds_read_b128 v[218:221], v216 offset:21504
	ds_read_b128 v[226:229], v216 offset:23552
	global_load_lds_dwordx4 v150, s[10:11]
	v_lshl_add_u64 v[250:251], s[10:11], 0, v[152:153]
	s_mov_b32 m0, s51
	s_nop 0
	global_load_lds_dwordx4 v152, s[10:11]
	s_waitcnt vmcnt(10)
	s_waitcnt lgkmcnt(4)
	s_barrier
	v_mfma_f32_16x16x32_bf16 v[60:63], v[128:131], v[170:173], v[60:63]
	v_mfma_f32_16x16x32_bf16 v[56:59], v[162:165], v[170:173], v[56:59]
	v_mfma_f32_16x16x32_bf16 v[44:47], v[128:131], v[178:181], v[44:47]
	v_mfma_f32_16x16x32_bf16 v[40:43], v[162:165], v[178:181], v[40:43]
	v_mfma_f32_16x16x32_bf16 v[28:31], v[128:131], v[186:189], v[28:31]
	v_mfma_f32_16x16x32_bf16 v[24:27], v[162:165], v[186:189], v[24:27]
	v_mfma_f32_16x16x32_bf16 v[12:15], v[128:131], v[222:225], v[12:15]
	v_mfma_f32_16x16x32_bf16 v[8:11], v[162:165], v[222:225], v[8:11]
	s_waitcnt lgkmcnt(0)
	v_mfma_f32_16x16x32_bf16 v[60:63], v[158:161], v[174:177], v[60:63]
	v_mfma_f32_16x16x32_bf16 v[56:59], v[166:169], v[174:177], v[56:59]
	v_mfma_f32_16x16x32_bf16 v[44:47], v[158:161], v[182:185], v[44:47]
	v_mfma_f32_16x16x32_bf16 v[40:43], v[166:169], v[182:185], v[40:43]
	v_mfma_f32_16x16x32_bf16 v[28:31], v[158:161], v[218:221], v[28:31]
	v_mfma_f32_16x16x32_bf16 v[24:27], v[166:169], v[218:221], v[24:27]
	v_mfma_f32_16x16x32_bf16 v[12:15], v[158:161], v[226:229], v[12:15]
	v_mfma_f32_16x16x32_bf16 v[8:11], v[166:169], v[226:229], v[8:11]
	s_barrier
	s_add_u32 s30, s6, 0x40000
	s_addc_u32 s31, s7, 0
	s_add_i32 s29, s34, s15
	s_mov_b32 m0, s29
	s_nop 0
	global_load_lds_dwordx4 v150, s[30:31]
	s_add_i32 m0, s29, 0x2000
	s_nop 0
	global_load_lds_dwordx4 v152, s[30:31]
	v_add_u32_e32 v166, 0x18000, v215
	ds_read_b128 v[128:131], v166
	ds_read_b128 v[158:161], v166 offset:1024
	ds_read_b128 v[162:165], v166 offset:2048
	ds_read_b128 v[166:169], v166 offset:3072
	s_waitcnt vmcnt(10)
	s_barrier
	v_mfma_f32_16x16x32_bf16 v[52:55], v[230:233], v[170:173], v[52:55]
	v_mfma_f32_16x16x32_bf16 v[48:51], v[238:241], v[170:173], v[48:51]
	v_mfma_f32_16x16x32_bf16 v[36:39], v[230:233], v[178:181], v[36:39]
	v_mfma_f32_16x16x32_bf16 v[32:35], v[238:241], v[178:181], v[32:35]
	v_mfma_f32_16x16x32_bf16 v[20:23], v[230:233], v[186:189], v[20:23]
	v_mfma_f32_16x16x32_bf16 v[16:19], v[238:241], v[186:189], v[16:19]
	v_mfma_f32_16x16x32_bf16 v[4:7], v[230:233], v[222:225], v[4:7]
	v_mfma_f32_16x16x32_bf16 v[0:3], v[238:241], v[222:225], v[0:3]
	v_mfma_f32_16x16x32_bf16 v[52:55], v[234:237], v[174:177], v[52:55]
	v_mfma_f32_16x16x32_bf16 v[48:51], v[242:245], v[174:177], v[48:51]
	v_mfma_f32_16x16x32_bf16 v[36:39], v[234:237], v[182:185], v[36:39]
	v_mfma_f32_16x16x32_bf16 v[32:35], v[242:245], v[182:185], v[32:35]
	v_mfma_f32_16x16x32_bf16 v[20:23], v[234:237], v[218:221], v[20:23]
	v_mfma_f32_16x16x32_bf16 v[16:19], v[242:245], v[218:221], v[16:19]
	v_mfma_f32_16x16x32_bf16 v[4:7], v[234:237], v[226:229], v[4:7]
	v_mfma_f32_16x16x32_bf16 v[0:3], v[242:245], v[226:229], v[0:3]
	s_add_i32 s29, 0, 0x18000
	s_barrier
	s_add_u32 s10, s10, 0x40000
	s_addc_u32 s11, s11, 0
	s_mov_b32 m0, s36
	ds_read_b128 v[170:173], v216 offset:32768
	ds_read_b128 v[178:181], v216 offset:34816
	ds_read_b128 v[186:189], v216 offset:36864
	ds_read_b128 v[222:225], v216 offset:38912
	ds_read_b128 v[174:177], v216 offset:33792
	ds_read_b128 v[182:185], v216 offset:35840
	ds_read_b128 v[218:221], v216 offset:37888
	ds_read_b128 v[226:229], v216 offset:39936
	global_load_lds_dwordx4 v150, s[10:11]
	s_mov_b32 m0, s37
	s_nop 0
	global_load_lds_dwordx4 v152, s[10:11]
	s_waitcnt lgkmcnt(8)
	s_waitcnt vmcnt(10)
	s_waitcnt lgkmcnt(4)
	s_barrier
	v_mfma_f32_16x16x32_bf16 v[124:127], v[128:131], v[170:173], v[124:127]
	v_mfma_f32_16x16x32_bf16 v[120:123], v[162:165], v[170:173], v[120:123]
	v_mfma_f32_16x16x32_bf16 v[108:111], v[128:131], v[178:181], v[108:111]
	v_mfma_f32_16x16x32_bf16 v[104:107], v[162:165], v[178:181], v[104:107]
	v_mfma_f32_16x16x32_bf16 v[92:95], v[128:131], v[186:189], v[92:95]
	v_mfma_f32_16x16x32_bf16 v[88:91], v[162:165], v[186:189], v[88:91]
	v_mfma_f32_16x16x32_bf16 v[76:79], v[128:131], v[222:225], v[76:79]
	v_mfma_f32_16x16x32_bf16 v[72:75], v[162:165], v[222:225], v[72:75]
	s_waitcnt lgkmcnt(0)
	v_mfma_f32_16x16x32_bf16 v[124:127], v[158:161], v[174:177], v[124:127]
	v_mfma_f32_16x16x32_bf16 v[120:123], v[166:169], v[174:177], v[120:123]
	v_mfma_f32_16x16x32_bf16 v[108:111], v[158:161], v[182:185], v[108:111]
	v_mfma_f32_16x16x32_bf16 v[104:107], v[166:169], v[182:185], v[104:107]
	v_mfma_f32_16x16x32_bf16 v[92:95], v[158:161], v[218:221], v[92:95]
	v_mfma_f32_16x16x32_bf16 v[88:91], v[166:169], v[218:221], v[88:91]
	v_mfma_f32_16x16x32_bf16 v[76:79], v[158:161], v[226:229], v[76:79]
	v_mfma_f32_16x16x32_bf16 v[72:75], v[166:169], v[226:229], v[72:75]
	s_barrier
	s_add_i32 s10, 0, 0x1c000
	s_add_i32 s11, s29, s15
	v_add_u32_e32 v132, s10, v215
	s_mov_b32 m0, s11
	ds_read_b128 v[230:233], v132
	ds_read_b128 v[238:241], v132 offset:2048
	ds_read_b128 v[234:237], v132 offset:1024
	ds_read_b128 v[242:245], v132 offset:3072
	s_add_u32 s98, s6, 0x80
	s_addc_u32 s99, s7, 0
	global_load_lds_dwordx4 v150, s[98:99]
	s_add_i32 m0, s11, 0x2000
	s_nop 0
	global_load_lds_dwordx4 v152, s[98:99]
	s_waitcnt vmcnt(10)
	s_waitcnt lgkmcnt(2)
	s_barrier
	v_mfma_f32_16x16x32_bf16 v[116:119], v[230:233], v[170:173], v[116:119]
	v_mfma_f32_16x16x32_bf16 v[112:115], v[238:241], v[170:173], v[112:115]
	v_mfma_f32_16x16x32_bf16 v[100:103], v[230:233], v[178:181], v[100:103]
	v_mfma_f32_16x16x32_bf16 v[96:99], v[238:241], v[178:181], v[96:99]
	v_mfma_f32_16x16x32_bf16 v[84:87], v[230:233], v[186:189], v[84:87]
	v_mfma_f32_16x16x32_bf16 v[80:83], v[238:241], v[186:189], v[80:83]
	v_mfma_f32_16x16x32_bf16 v[68:71], v[230:233], v[222:225], v[68:71]
	v_mfma_f32_16x16x32_bf16 v[64:67], v[238:241], v[222:225], v[64:67]
	s_waitcnt lgkmcnt(0)
	v_mfma_f32_16x16x32_bf16 v[116:119], v[234:237], v[174:177], v[116:119]
	v_mfma_f32_16x16x32_bf16 v[112:115], v[242:245], v[174:177], v[112:115]
	v_mfma_f32_16x16x32_bf16 v[100:103], v[234:237], v[182:185], v[100:103]
	v_mfma_f32_16x16x32_bf16 v[96:99], v[242:245], v[182:185], v[96:99]
	v_mfma_f32_16x16x32_bf16 v[84:87], v[234:237], v[218:221], v[84:87]
	v_mfma_f32_16x16x32_bf16 v[80:83], v[242:245], v[218:221], v[80:83]
	v_mfma_f32_16x16x32_bf16 v[68:71], v[234:237], v[226:229], v[68:71]
	v_mfma_f32_16x16x32_bf16 v[64:67], v[242:245], v[226:229], v[64:67]
	s_mov_b32 m0, s52
	v_lshl_add_u64 v[190:191], v[248:249], 0, s[66:67]
	s_barrier
	ds_read_b128 v[170:173], v216 offset:49152
	ds_read_b128 v[178:181], v216 offset:51200
	ds_read_b128 v[186:189], v216 offset:53248
	ds_read_b128 v[222:225], v216 offset:55296
	ds_read_b128 v[174:177], v216 offset:50176
	ds_read_b128 v[182:185], v216 offset:52224
	ds_read_b128 v[218:221], v216 offset:54272
	ds_read_b128 v[226:229], v216 offset:56320
	global_load_lds_dwordx4 v[190:191], off
	v_lshl_add_u64 v[190:191], v[250:251], 0, s[66:67]
	s_mov_b32 m0, s53
	s_nop 0
	global_load_lds_dwordx4 v[190:191], off
	s_waitcnt vmcnt(10)
	s_waitcnt lgkmcnt(4)
	s_barrier
	v_mfma_f32_16x16x32_bf16 v[60:63], v[128:131], v[170:173], v[60:63]
	v_mfma_f32_16x16x32_bf16 v[56:59], v[162:165], v[170:173], v[56:59]
	v_mfma_f32_16x16x32_bf16 v[44:47], v[128:131], v[178:181], v[44:47]
	v_mfma_f32_16x16x32_bf16 v[40:43], v[162:165], v[178:181], v[40:43]
	v_mfma_f32_16x16x32_bf16 v[28:31], v[128:131], v[186:189], v[28:31]
	v_mfma_f32_16x16x32_bf16 v[24:27], v[162:165], v[186:189], v[24:27]
	v_mfma_f32_16x16x32_bf16 v[12:15], v[128:131], v[222:225], v[12:15]
	v_mfma_f32_16x16x32_bf16 v[8:11], v[162:165], v[222:225], v[8:11]
	s_waitcnt lgkmcnt(0)
	v_mfma_f32_16x16x32_bf16 v[60:63], v[158:161], v[174:177], v[60:63]
	v_mfma_f32_16x16x32_bf16 v[56:59], v[166:169], v[174:177], v[56:59]
	v_mfma_f32_16x16x32_bf16 v[44:47], v[158:161], v[182:185], v[44:47]
	v_mfma_f32_16x16x32_bf16 v[40:43], v[166:169], v[182:185], v[40:43]
	v_mfma_f32_16x16x32_bf16 v[28:31], v[158:161], v[218:221], v[28:31]
	v_mfma_f32_16x16x32_bf16 v[24:27], v[166:169], v[218:221], v[24:27]
	v_mfma_f32_16x16x32_bf16 v[12:15], v[158:161], v[226:229], v[12:15]
	v_mfma_f32_16x16x32_bf16 v[8:11], v[166:169], v[226:229], v[8:11]
	s_barrier
	s_add_u32 s6, s6, 0x40080
	s_addc_u32 s7, s7, 0
	s_add_i32 s10, s10, s15
	s_mov_b32 m0, s10
	s_nop 0
	global_load_lds_dwordx4 v150, s[6:7]
	s_add_i32 m0, s10, 0x2000
	s_nop 0
	global_load_lds_dwordx4 v152, s[6:7]
	v_add_u32_e32 v166, 0x10000, v215
	ds_read_b128 v[128:131], v166
	ds_read_b128 v[158:161], v166 offset:1024
	ds_read_b128 v[162:165], v166 offset:2048
	ds_read_b128 v[166:169], v166 offset:3072
	s_waitcnt vmcnt(10)
	s_barrier
	v_mfma_f32_16x16x32_bf16 v[52:55], v[230:233], v[170:173], v[52:55]
	v_mfma_f32_16x16x32_bf16 v[48:51], v[238:241], v[170:173], v[48:51]
	v_mfma_f32_16x16x32_bf16 v[36:39], v[230:233], v[178:181], v[36:39]
	v_mfma_f32_16x16x32_bf16 v[32:35], v[238:241], v[178:181], v[32:35]
	v_mfma_f32_16x16x32_bf16 v[20:23], v[230:233], v[186:189], v[20:23]
	v_mfma_f32_16x16x32_bf16 v[16:19], v[238:241], v[186:189], v[16:19]
	v_mfma_f32_16x16x32_bf16 v[4:7], v[230:233], v[222:225], v[4:7]
	v_mfma_f32_16x16x32_bf16 v[0:3], v[238:241], v[222:225], v[0:3]
	v_mfma_f32_16x16x32_bf16 v[52:55], v[234:237], v[174:177], v[52:55]
	v_mfma_f32_16x16x32_bf16 v[48:51], v[242:245], v[174:177], v[48:51]
	v_mfma_f32_16x16x32_bf16 v[36:39], v[234:237], v[182:185], v[36:39]
	v_mfma_f32_16x16x32_bf16 v[32:35], v[242:245], v[182:185], v[32:35]
	v_mfma_f32_16x16x32_bf16 v[20:23], v[234:237], v[218:221], v[20:23]
	v_mfma_f32_16x16x32_bf16 v[16:19], v[242:245], v[218:221], v[16:19]
	v_mfma_f32_16x16x32_bf16 v[4:7], v[234:237], v[226:229], v[4:7]
	v_mfma_f32_16x16x32_bf16 v[0:3], v[242:245], v[226:229], v[0:3]
	s_add_i32 s28, s28, 2
	s_add_u32 s2, s2, 0x100
	s_addc_u32 s3, s3, 0
	s_add_u32 s19, s19, 0x100
	s_addc_u32 s27, s27, 0
	s_cmp_gt_u32 s28, 13
	s_barrier
	s_cbranch_scc0 .LBB0_145
	s_waitcnt lgkmcnt(0)
	v_mov_b32_e32 v166, v135
	s_mov_b64 s[2:3], s[0:1]
	v_readfirstlane_b32 s27, v166
	s_bfe_u32 s19, s27, 0x20006
	s_load_dwordx2 s[30:31], s[2:3], 0x88
	s_mov_b64 s[2:3], s[0:1]
	s_cmp_gt_i32 s8, 31
	s_load_dwordx2 s[28:29], s[2:3], 0x80
	s_cselect_b64 s[6:7], -1, 0
	s_cmp_lt_i32 s8, 32
	s_cselect_b64 s[2:3], -1, 0
	s_ashr_i32 s9, s27, 2
	s_lshl_b32 s8, s8, 8
	s_and_b32 s17, s9, 0xffffffc0
	v_and_b32_e32 v217, 15, v166
	s_add_i32 s17, s17, s8
	v_bfe_u32 v186, v166, 4, 2
	v_or_b32_e32 v158, s17, v217
	s_cmp_gt_i32 s26, 3
	s_mov_b64 s[8:9], -1
	s_cbranch_scc0 .LBB0_829
	s_cmp_gt_u32 s26, 5
	s_cbranch_scc0 .LBB0_409
	s_cmp_gt_u32 s26, 8
	s_cbranch_scc0 .LBB0_406
	s_waitcnt lgkmcnt(0)
	v_and_b32_e32 v128, 1, v166
	v_cmp_eq_u32_e64 s[8:9], 0, v128
	v_cmp_eq_u32_e32 vcc, 1, v128
	s_mov_b32 s10, 0x05040100
	s_mov_b32 s11, 0x07060302
	s_cmp_eq_u32 s6, 0
	s_cbranch_scc1 .Lvf_f_c

.LBB0_1104:
	s_add_u32 s22, s18, 0xfffc0080
	s_addc_u32 s23, s19, -1
	s_add_i32 s47, 0, 0x10000
	s_cmp_eq_u32 s46, 12
	s_cselect_b32 s25, s9, s23
	s_cselect_b32 s24, s42, s22
	s_cselect_b32 s23, s7, s45
	s_cselect_b32 s22, s43, s44
	s_add_i32 m0, s17, 0xc000
	ds_read_b128 v[172:175], v155
	ds_read_b128 v[180:183], v155 offset:2048
	ds_read_b128 v[188:191], v155 offset:4096
	ds_read_b128 v[220:223], v155 offset:6144
	ds_read_b128 v[176:179], v155 offset:1024
	ds_read_b128 v[184:187], v155 offset:3072
	ds_read_b128 v[216:219], v155 offset:5120
	ds_read_b128 v[224:227], v155 offset:7168
	global_load_lds_dwordx4 v130, s[18:19]
	s_add_i32 m0, s17, 0xe000
	s_nop 0
	global_load_lds_dwordx4 v150, s[18:19]
	s_waitcnt lgkmcnt(8)
	s_waitcnt vmcnt(10)
	s_waitcnt lgkmcnt(4)
	s_barrier
	v_mfma_f32_16x16x32_bf16 v[124:127], v[156:159], v[172:175], v[124:127]
	v_mfma_f32_16x16x32_bf16 v[120:123], v[164:167], v[172:175], v[120:123]
	v_mfma_f32_16x16x32_bf16 v[108:111], v[156:159], v[180:183], v[108:111]
	v_mfma_f32_16x16x32_bf16 v[104:107], v[164:167], v[180:183], v[104:107]
	v_mfma_f32_16x16x32_bf16 v[92:95], v[156:159], v[188:191], v[92:95]
	v_mfma_f32_16x16x32_bf16 v[88:91], v[164:167], v[188:191], v[88:91]
	v_mfma_f32_16x16x32_bf16 v[76:79], v[156:159], v[220:223], v[76:79]
	v_mfma_f32_16x16x32_bf16 v[72:75], v[164:167], v[220:223], v[72:75]
	s_waitcnt lgkmcnt(0)
	v_mfma_f32_16x16x32_bf16 v[124:127], v[160:163], v[176:179], v[124:127]
	v_mfma_f32_16x16x32_bf16 v[120:123], v[168:171], v[176:179], v[120:123]
	v_mfma_f32_16x16x32_bf16 v[108:111], v[160:163], v[184:187], v[108:111]
	v_mfma_f32_16x16x32_bf16 v[104:107], v[168:171], v[184:187], v[104:107]
	v_mfma_f32_16x16x32_bf16 v[92:95], v[160:163], v[216:219], v[92:95]
	v_mfma_f32_16x16x32_bf16 v[88:91], v[168:171], v[216:219], v[88:91]
	v_mfma_f32_16x16x32_bf16 v[76:79], v[160:163], v[224:227], v[76:79]
	v_mfma_f32_16x16x32_bf16 v[72:75], v[168:171], v[224:227], v[72:75]
	s_barrier
	s_add_i32 s50, 0, 0x14000
	v_add_u32_e32 v152, s50, v154
	s_add_i32 s47, s47, s29
	ds_read_b128 v[228:231], v152
	ds_read_b128 v[236:239], v152 offset:2048
	ds_read_b128 v[232:235], v152 offset:1024
	ds_read_b128 v[240:243], v152 offset:3072
	s_mov_b32 m0, s47
	s_nop 0
	global_load_lds_dwordx4 v132, s[22:23]
	s_add_i32 m0, s47, 0x2000
	s_nop 0
	global_load_lds_dwordx4 v128, s[22:23]
	s_waitcnt vmcnt(10)
	s_waitcnt lgkmcnt(2)
	s_barrier
	v_mfma_f32_16x16x32_bf16 v[116:119], v[228:231], v[172:175], v[116:119]
	v_mfma_f32_16x16x32_bf16 v[112:115], v[236:239], v[172:175], v[112:115]
	v_mfma_f32_16x16x32_bf16 v[100:103], v[228:231], v[180:183], v[100:103]
	v_mfma_f32_16x16x32_bf16 v[96:99], v[236:239], v[180:183], v[96:99]
	v_mfma_f32_16x16x32_bf16 v[84:87], v[228:231], v[188:191], v[84:87]
	v_mfma_f32_16x16x32_bf16 v[80:83], v[236:239], v[188:191], v[80:83]
	v_mfma_f32_16x16x32_bf16 v[68:71], v[228:231], v[220:223], v[68:71]
	v_mfma_f32_16x16x32_bf16 v[64:67], v[236:239], v[220:223], v[64:67]
	s_waitcnt lgkmcnt(0)
	v_mfma_f32_16x16x32_bf16 v[116:119], v[232:235], v[176:179], v[116:119]
	v_mfma_f32_16x16x32_bf16 v[112:115], v[240:243], v[176:179], v[112:115]
	v_mfma_f32_16x16x32_bf16 v[100:103], v[232:235], v[184:187], v[100:103]
	v_mfma_f32_16x16x32_bf16 v[96:99], v[240:243], v[184:187], v[96:99]
	v_mfma_f32_16x16x32_bf16 v[84:87], v[232:235], v[216:219], v[84:87]
	v_mfma_f32_16x16x32_bf16 v[80:83], v[240:243], v[216:219], v[80:83]
	v_mfma_f32_16x16x32_bf16 v[68:71], v[232:235], v[224:227], v[68:71]
	v_mfma_f32_16x16x32_bf16 v[64:67], v[240:243], v[224:227], v[64:67]
	s_mov_b32 m0, s17
	v_lshl_add_u64 v[246:247], s[24:25], 0, v[132:133]
	s_barrier
	ds_read_b128 v[172:175], v155 offset:16384
	ds_read_b128 v[180:183], v155 offset:18432
	ds_read_b128 v[188:191], v155 offset:20480
	ds_read_b128 v[220:223], v155 offset:22528
	ds_read_b128 v[176:179], v155 offset:17408
	ds_read_b128 v[184:187], v155 offset:19456
	ds_read_b128 v[216:219], v155 offset:21504
	ds_read_b128 v[224:227], v155 offset:23552
	global_load_lds_dwordx4 v132, s[24:25]
	v_lshl_add_u64 v[248:249], s[24:25], 0, v[128:129]
	s_mov_b32 m0, s31
	s_nop 0
	global_load_lds_dwordx4 v128, s[24:25]
	s_waitcnt vmcnt(10)
	s_waitcnt lgkmcnt(4)
	s_barrier
	v_mfma_f32_16x16x32_bf16 v[60:63], v[156:159], v[172:175], v[60:63]
	v_mfma_f32_16x16x32_bf16 v[56:59], v[164:167], v[172:175], v[56:59]
	v_mfma_f32_16x16x32_bf16 v[44:47], v[156:159], v[180:183], v[44:47]
	v_mfma_f32_16x16x32_bf16 v[40:43], v[164:167], v[180:183], v[40:43]
	v_mfma_f32_16x16x32_bf16 v[28:31], v[156:159], v[188:191], v[28:31]
	v_mfma_f32_16x16x32_bf16 v[24:27], v[164:167], v[188:191], v[24:27]
	v_mfma_f32_16x16x32_bf16 v[12:15], v[156:159], v[220:223], v[12:15]
	v_mfma_f32_16x16x32_bf16 v[8:11], v[164:167], v[220:223], v[8:11]
	s_waitcnt lgkmcnt(0)
	v_mfma_f32_16x16x32_bf16 v[60:63], v[160:163], v[176:179], v[60:63]
	v_mfma_f32_16x16x32_bf16 v[56:59], v[168:171], v[176:179], v[56:59]
	v_mfma_f32_16x16x32_bf16 v[44:47], v[160:163], v[184:187], v[44:47]
	v_mfma_f32_16x16x32_bf16 v[40:43], v[168:171], v[184:187], v[40:43]
	v_mfma_f32_16x16x32_bf16 v[28:31], v[160:163], v[216:219], v[28:31]
	v_mfma_f32_16x16x32_bf16 v[24:27], v[168:171], v[216:219], v[24:27]
	v_mfma_f32_16x16x32_bf16 v[12:15], v[160:163], v[224:227], v[12:15]
	v_mfma_f32_16x16x32_bf16 v[8:11], v[168:171], v[224:227], v[8:11]
	s_barrier
	s_add_u32 s48, s22, 0x40000
	s_addc_u32 s49, s23, 0
	s_add_i32 s47, s50, s29
	s_mov_b32 m0, s47
	s_nop 0
	global_load_lds_dwordx4 v132, s[48:49]
	s_add_i32 m0, s47, 0x2000
	s_nop 0
	global_load_lds_dwordx4 v128, s[48:49]
	v_add_u32_e32 v168, 0x18000, v154
	ds_read_b128 v[156:159], v168
	ds_read_b128 v[160:163], v168 offset:1024
	ds_read_b128 v[164:167], v168 offset:2048
	ds_read_b128 v[168:171], v168 offset:3072
	s_waitcnt vmcnt(10)
	s_barrier
	v_mfma_f32_16x16x32_bf16 v[52:55], v[228:231], v[172:175], v[52:55]
	v_mfma_f32_16x16x32_bf16 v[48:51], v[236:239], v[172:175], v[48:51]
	v_mfma_f32_16x16x32_bf16 v[36:39], v[228:231], v[180:183], v[36:39]
	v_mfma_f32_16x16x32_bf16 v[32:35], v[236:239], v[180:183], v[32:35]
	v_mfma_f32_16x16x32_bf16 v[20:23], v[228:231], v[188:191], v[20:23]
	v_mfma_f32_16x16x32_bf16 v[16:19], v[236:239], v[188:191], v[16:19]
	v_mfma_f32_16x16x32_bf16 v[4:7], v[228:231], v[220:223], v[4:7]
	v_mfma_f32_16x16x32_bf16 v[0:3], v[236:239], v[220:223], v[0:3]
	v_mfma_f32_16x16x32_bf16 v[52:55], v[232:235], v[176:179], v[52:55]
	v_mfma_f32_16x16x32_bf16 v[48:51], v[240:243], v[176:179], v[48:51]
	v_mfma_f32_16x16x32_bf16 v[36:39], v[232:235], v[184:187], v[36:39]
	v_mfma_f32_16x16x32_bf16 v[32:35], v[240:243], v[184:187], v[32:35]
	v_mfma_f32_16x16x32_bf16 v[20:23], v[232:235], v[216:219], v[20:23]
	v_mfma_f32_16x16x32_bf16 v[16:19], v[240:243], v[216:219], v[16:19]
	v_mfma_f32_16x16x32_bf16 v[4:7], v[232:235], v[224:227], v[4:7]
	v_mfma_f32_16x16x32_bf16 v[0:3], v[240:243], v[224:227], v[0:3]
	s_add_i32 s47, 0, 0x18000
	s_barrier
	s_add_u32 s24, s24, 0x40000
	s_addc_u32 s25, s25, 0
	s_mov_b32 m0, s34
	ds_read_b128 v[172:175], v155 offset:32768
	ds_read_b128 v[180:183], v155 offset:34816
	ds_read_b128 v[188:191], v155 offset:36864
	ds_read_b128 v[220:223], v155 offset:38912
	ds_read_b128 v[176:179], v155 offset:33792
	ds_read_b128 v[184:187], v155 offset:35840
	ds_read_b128 v[216:219], v155 offset:37888
	ds_read_b128 v[224:227], v155 offset:39936
	global_load_lds_dwordx4 v132, s[24:25]
	s_mov_b32 m0, s35
	s_nop 0
	global_load_lds_dwordx4 v128, s[24:25]
	s_waitcnt lgkmcnt(8)
	s_waitcnt vmcnt(10)
	s_waitcnt lgkmcnt(4)
	s_barrier
	v_mfma_f32_16x16x32_bf16 v[124:127], v[156:159], v[172:175], v[124:127]
	v_mfma_f32_16x16x32_bf16 v[120:123], v[164:167], v[172:175], v[120:123]
	v_mfma_f32_16x16x32_bf16 v[108:111], v[156:159], v[180:183], v[108:111]
	v_mfma_f32_16x16x32_bf16 v[104:107], v[164:167], v[180:183], v[104:107]
	v_mfma_f32_16x16x32_bf16 v[92:95], v[156:159], v[188:191], v[92:95]
	v_mfma_f32_16x16x32_bf16 v[88:91], v[164:167], v[188:191], v[88:91]
	v_mfma_f32_16x16x32_bf16 v[76:79], v[156:159], v[220:223], v[76:79]
	v_mfma_f32_16x16x32_bf16 v[72:75], v[164:167], v[220:223], v[72:75]
	s_waitcnt lgkmcnt(0)
	v_mfma_f32_16x16x32_bf16 v[124:127], v[160:163], v[176:179], v[124:127]
	v_mfma_f32_16x16x32_bf16 v[120:123], v[168:171], v[176:179], v[120:123]
	v_mfma_f32_16x16x32_bf16 v[108:111], v[160:163], v[184:187], v[108:111]
	v_mfma_f32_16x16x32_bf16 v[104:107], v[168:171], v[184:187], v[104:107]
	v_mfma_f32_16x16x32_bf16 v[92:95], v[160:163], v[216:219], v[92:95]
	v_mfma_f32_16x16x32_bf16 v[88:91], v[168:171], v[216:219], v[88:91]
	v_mfma_f32_16x16x32_bf16 v[76:79], v[160:163], v[224:227], v[76:79]
	v_mfma_f32_16x16x32_bf16 v[72:75], v[168:171], v[224:227], v[72:75]
	s_barrier
	s_add_i32 s24, 0, 0x1c000
	s_add_i32 s25, s47, s29
	v_add_u32_e32 v200, s24, v154
	s_mov_b32 m0, s25
	ds_read_b128 v[228:231], v200
	ds_read_b128 v[236:239], v200 offset:2048
	ds_read_b128 v[232:235], v200 offset:1024
	ds_read_b128 v[240:243], v200 offset:3072
	s_add_u32 s98, s22, 0x80
	s_addc_u32 s99, s23, 0
	global_load_lds_dwordx4 v132, s[98:99]
	s_add_i32 m0, s25, 0x2000
	s_nop 0
	global_load_lds_dwordx4 v128, s[98:99]
	s_waitcnt vmcnt(10)
	s_waitcnt lgkmcnt(2)
	s_barrier
	v_mfma_f32_16x16x32_bf16 v[116:119], v[228:231], v[172:175], v[116:119]
	v_mfma_f32_16x16x32_bf16 v[112:115], v[236:239], v[172:175], v[112:115]
	v_mfma_f32_16x16x32_bf16 v[100:103], v[228:231], v[180:183], v[100:103]
	v_mfma_f32_16x16x32_bf16 v[96:99], v[236:239], v[180:183], v[96:99]
	v_mfma_f32_16x16x32_bf16 v[84:87], v[228:231], v[188:191], v[84:87]
	v_mfma_f32_16x16x32_bf16 v[80:83], v[236:239], v[188:191], v[80:83]
	v_mfma_f32_16x16x32_bf16 v[68:71], v[228:231], v[220:223], v[68:71]
	v_mfma_f32_16x16x32_bf16 v[64:67], v[236:239], v[220:223], v[64:67]
	s_waitcnt lgkmcnt(0)
	v_mfma_f32_16x16x32_bf16 v[116:119], v[232:235], v[176:179], v[116:119]
	v_mfma_f32_16x16x32_bf16 v[112:115], v[240:243], v[176:179], v[112:115]
	v_mfma_f32_16x16x32_bf16 v[100:103], v[232:235], v[184:187], v[100:103]
	v_mfma_f32_16x16x32_bf16 v[96:99], v[240:243], v[184:187], v[96:99]
	v_mfma_f32_16x16x32_bf16 v[84:87], v[232:235], v[216:219], v[84:87]
	v_mfma_f32_16x16x32_bf16 v[80:83], v[240:243], v[216:219], v[80:83]
	v_mfma_f32_16x16x32_bf16 v[68:71], v[232:235], v[224:227], v[68:71]
	v_mfma_f32_16x16x32_bf16 v[64:67], v[240:243], v[224:227], v[64:67]
	s_mov_b32 m0, s36
	v_lshl_add_u64 v[152:153], v[246:247], 0, s[66:67]
	s_barrier
	ds_read_b128 v[172:175], v155 offset:49152
	ds_read_b128 v[180:183], v155 offset:51200
	ds_read_b128 v[188:191], v155 offset:53248
	ds_read_b128 v[220:223], v155 offset:55296
	ds_read_b128 v[176:179], v155 offset:50176
	ds_read_b128 v[184:187], v155 offset:52224
	ds_read_b128 v[216:219], v155 offset:54272
	ds_read_b128 v[224:227], v155 offset:56320
	global_load_lds_dwordx4 v[152:153], off
	v_lshl_add_u64 v[152:153], v[248:249], 0, s[66:67]
	s_mov_b32 m0, s37
	s_nop 0
	global_load_lds_dwordx4 v[152:153], off
	s_waitcnt vmcnt(10)
	s_waitcnt lgkmcnt(4)
	s_barrier
	v_mfma_f32_16x16x32_bf16 v[60:63], v[156:159], v[172:175], v[60:63]
	v_mfma_f32_16x16x32_bf16 v[56:59], v[164:167], v[172:175], v[56:59]
	v_mfma_f32_16x16x32_bf16 v[44:47], v[156:159], v[180:183], v[44:47]
	v_mfma_f32_16x16x32_bf16 v[40:43], v[164:167], v[180:183], v[40:43]
	v_mfma_f32_16x16x32_bf16 v[28:31], v[156:159], v[188:191], v[28:31]
	v_mfma_f32_16x16x32_bf16 v[24:27], v[164:167], v[188:191], v[24:27]
	v_mfma_f32_16x16x32_bf16 v[12:15], v[156:159], v[220:223], v[12:15]
	v_mfma_f32_16x16x32_bf16 v[8:11], v[164:167], v[220:223], v[8:11]
	s_waitcnt lgkmcnt(0)
	v_mfma_f32_16x16x32_bf16 v[60:63], v[160:163], v[176:179], v[60:63]
	v_mfma_f32_16x16x32_bf16 v[56:59], v[168:171], v[176:179], v[56:59]
	v_mfma_f32_16x16x32_bf16 v[44:47], v[160:163], v[184:187], v[44:47]
	v_mfma_f32_16x16x32_bf16 v[40:43], v[168:171], v[184:187], v[40:43]
	v_mfma_f32_16x16x32_bf16 v[28:31], v[160:163], v[216:219], v[28:31]
	v_mfma_f32_16x16x32_bf16 v[24:27], v[168:171], v[216:219], v[24:27]
	v_mfma_f32_16x16x32_bf16 v[12:15], v[160:163], v[224:227], v[12:15]
	v_mfma_f32_16x16x32_bf16 v[8:11], v[168:171], v[224:227], v[8:11]
	s_barrier
	s_add_u32 s22, s22, 0x40080
	s_addc_u32 s23, s23, 0
	s_add_i32 s24, s24, s29
	s_mov_b32 m0, s24
	s_nop 0
	global_load_lds_dwordx4 v132, s[22:23]
	s_add_i32 m0, s24, 0x2000
	s_nop 0
	global_load_lds_dwordx4 v128, s[22:23]
	v_add_u32_e32 v168, 0x10000, v154
	ds_read_b128 v[156:159], v168
	ds_read_b128 v[160:163], v168 offset:1024
	ds_read_b128 v[164:167], v168 offset:2048
	ds_read_b128 v[168:171], v168 offset:3072
	s_waitcnt vmcnt(10)
	s_barrier
	v_mfma_f32_16x16x32_bf16 v[52:55], v[228:231], v[172:175], v[52:55]
	v_mfma_f32_16x16x32_bf16 v[48:51], v[236:239], v[172:175], v[48:51]
	v_mfma_f32_16x16x32_bf16 v[36:39], v[228:231], v[180:183], v[36:39]
	v_mfma_f32_16x16x32_bf16 v[32:35], v[236:239], v[180:183], v[32:35]
	v_mfma_f32_16x16x32_bf16 v[20:23], v[228:231], v[188:191], v[20:23]
	v_mfma_f32_16x16x32_bf16 v[16:19], v[236:239], v[188:191], v[16:19]
	v_mfma_f32_16x16x32_bf16 v[4:7], v[228:231], v[220:223], v[4:7]
	v_mfma_f32_16x16x32_bf16 v[0:3], v[236:239], v[220:223], v[0:3]
	v_mfma_f32_16x16x32_bf16 v[52:55], v[232:235], v[176:179], v[52:55]
	v_mfma_f32_16x16x32_bf16 v[48:51], v[240:243], v[176:179], v[48:51]
	v_mfma_f32_16x16x32_bf16 v[36:39], v[232:235], v[184:187], v[36:39]
	v_mfma_f32_16x16x32_bf16 v[32:35], v[240:243], v[184:187], v[32:35]
	v_mfma_f32_16x16x32_bf16 v[20:23], v[232:235], v[216:219], v[20:23]
	v_mfma_f32_16x16x32_bf16 v[16:19], v[240:243], v[216:219], v[16:19]
	v_mfma_f32_16x16x32_bf16 v[4:7], v[232:235], v[224:227], v[4:7]
	v_mfma_f32_16x16x32_bf16 v[0:3], v[240:243], v[224:227], v[0:3]
	s_add_i32 s46, s46, 2
	s_add_u32 s18, s18, 0x100
	s_addc_u32 s19, s19, 0
	s_add_u32 s44, s44, 0x100
	s_addc_u32 s45, s45, 0
	s_cmp_gt_u32 s46, 13
	s_barrier
	s_cbranch_scc0 .LBB0_1104
	s_waitcnt lgkmcnt(0)
	v_mov_b32_e32 v153, v135
	s_mov_b64 s[18:19], s[0:1]
	s_load_dwordx2 s[18:19], s[18:19], 0x88
	s_nop 0
	v_readfirstlane_b32 s7, v153
	s_ashr_i32 s9, s7, 2
	s_lshr_b32 s7, s7, 1
	s_lshl_b32 s22, s41, 7
	s_and_b32 s7, s7, 0x60
	s_andn2_b32 s9, s9, 63
	s_or_b32 s7, s7, s22
	v_lshrrev_b32_e32 v152, 1, v153
	v_and_or_b32 v152, v152, 24, s7
	v_and_or_b32 v153, v153, 15, s9
	v_lshl_add_u32 v156, s16, 8, v153
	v_ashrrev_i32_e32 v153, 31, v152
	v_mov_b32_e32 v168, 0xbfb8aa3b
	v_mov_b32_e32 v169, 0xbfb8aa3b
	v_mov_b32_e32 v170, 1.0
	v_mov_b32_e32 v171, 1.0
	v_pk_mul_f32 v[160:161], v[124:125], v[168:169]
	v_pk_mul_f32 v[162:163], v[126:127], v[168:169]
	v_pk_mul_f32 v[164:165], v[116:117], v[168:169]
	v_pk_mul_f32 v[166:167], v[118:119], v[168:169]
	v_exp_f32_e32 v160, v160
	v_exp_f32_e32 v161, v161
	v_exp_f32_e32 v162, v162
	v_exp_f32_e32 v163, v163
	v_exp_f32_e32 v164, v164
	v_exp_f32_e32 v165, v165
	v_exp_f32_e32 v166, v166
	v_exp_f32_e32 v167, v167
	s_waitcnt lgkmcnt(0)
	v_lshl_add_u64 v[152:153], v[152:153], 1, s[18:19]
	s_mov_b64 s[18:19], 0xa2a4400
	v_lshl_add_u64 v[152:153], v[152:153], 0, s[18:19]
	s_and_b64 vcc, exec, s[4:5]
	s_mov_b32 s41, s6
	s_mov_b32 s16, s8
	s_mov_b64 s[22:23], s[12:13]
	v_pk_add_f32 v[160:161], v[160:161], v[170:171]
	v_pk_add_f32 v[162:163], v[162:163], v[170:171]
	v_pk_add_f32 v[164:165], v[164:165], v[170:171]
	v_pk_add_f32 v[166:167], v[166:167], v[170:171]
	v_rcp_f32_e32 v160, v160
	v_rcp_f32_e32 v161, v161
	v_rcp_f32_e32 v162, v162
	v_rcp_f32_e32 v163, v163
	v_rcp_f32_e32 v164, v164
	v_rcp_f32_e32 v165, v165
	v_rcp_f32_e32 v166, v166
	v_rcp_f32_e32 v167, v167
	v_mov_b32_e32 v158, v156
	v_mad_i64_i32 v[158:159], s[18:19], v158, s73, v[152:153]
	v_pk_mul_f32 v[124:125], v[124:125], v[160:161]
	v_pk_mul_f32 v[126:127], v[126:127], v[162:163]
	v_pk_mul_f32 v[116:117], v[116:117], v[164:165]
	v_pk_mul_f32 v[118:119], v[118:119], v[166:167]
	v_pk_mul_f32 v[120:121], v[120:121], v[124:125]
	v_pk_mul_f32 v[122:123], v[122:123], v[126:127]
	v_pk_mul_f32 v[112:113], v[112:113], v[116:117]
	v_pk_mul_f32 v[114:115], v[114:115], v[118:119]
	v_cvt_pk_bf16_f32 v120, v120, v121
	v_cvt_pk_bf16_f32 v121, v122, v123
	v_cvt_pk_bf16_f32 v122, v112, v113
	v_cvt_pk_bf16_f32 v123, v114, v115
	global_store_dwordx4 v[158:159], v[120:123], off sc1
	v_pk_mul_f32 v[160:161], v[108:109], v[168:169]
	v_pk_mul_f32 v[162:163], v[110:111], v[168:169]
	v_pk_mul_f32 v[164:165], v[100:101], v[168:169]
	v_pk_mul_f32 v[166:167], v[102:103], v[168:169]
	v_exp_f32_e32 v160, v160
	v_exp_f32_e32 v161, v161
	v_exp_f32_e32 v162, v162
	v_exp_f32_e32 v163, v163
	v_exp_f32_e32 v164, v164
	v_exp_f32_e32 v165, v165
	v_exp_f32_e32 v166, v166
	v_exp_f32_e32 v167, v167
	v_pk_add_f32 v[160:161], v[160:161], v[170:171]
	v_pk_add_f32 v[162:163], v[162:163], v[170:171]
	v_pk_add_f32 v[164:165], v[164:165], v[170:171]
	v_pk_add_f32 v[166:167], v[166:167], v[170:171]
	v_rcp_f32_e32 v160, v160
	v_rcp_f32_e32 v161, v161
	v_rcp_f32_e32 v162, v162
	v_rcp_f32_e32 v163, v163
	v_rcp_f32_e32 v164, v164
	v_rcp_f32_e32 v165, v165
	v_rcp_f32_e32 v166, v166
	v_rcp_f32_e32 v167, v167
	v_add_u32_e32 v158, 0x10, v156
	v_mad_i64_i32 v[158:159], s[18:19], v158, s73, v[152:153]
	v_pk_mul_f32 v[108:109], v[108:109], v[160:161]
	v_pk_mul_f32 v[110:111], v[110:111], v[162:163]
	v_pk_mul_f32 v[100:101], v[100:101], v[164:165]
	v_pk_mul_f32 v[102:103], v[102:103], v[166:167]
	v_pk_mul_f32 v[104:105], v[104:105], v[108:109]
	v_pk_mul_f32 v[106:107], v[106:107], v[110:111]
	v_pk_mul_f32 v[96:97], v[96:97], v[100:101]
	v_pk_mul_f32 v[98:99], v[98:99], v[102:103]
	v_cvt_pk_bf16_f32 v104, v104, v105
	v_cvt_pk_bf16_f32 v105, v106, v107
	v_cvt_pk_bf16_f32 v106, v96, v97
	v_cvt_pk_bf16_f32 v107, v98, v99
	global_store_dwordx4 v[158:159], v[104:107], off sc1
	v_pk_mul_f32 v[160:161], v[92:93], v[168:169]
	v_pk_mul_f32 v[162:163], v[94:95], v[168:169]
	v_pk_mul_f32 v[164:165], v[84:85], v[168:169]
	v_pk_mul_f32 v[166:167], v[86:87], v[168:169]
	v_exp_f32_e32 v160, v160
	v_exp_f32_e32 v161, v161
	v_exp_f32_e32 v162, v162
	v_exp_f32_e32 v163, v163
	v_exp_f32_e32 v164, v164
	v_exp_f32_e32 v165, v165
	v_exp_f32_e32 v166, v166
	v_exp_f32_e32 v167, v167
	v_pk_add_f32 v[160:161], v[160:161], v[170:171]
	v_pk_add_f32 v[162:163], v[162:163], v[170:171]
	v_pk_add_f32 v[164:165], v[164:165], v[170:171]
	v_pk_add_f32 v[166:167], v[166:167], v[170:171]
	v_rcp_f32_e32 v160, v160
	v_rcp_f32_e32 v161, v161
	v_rcp_f32_e32 v162, v162
	v_rcp_f32_e32 v163, v163
	v_rcp_f32_e32 v164, v164
	v_rcp_f32_e32 v165, v165
	v_rcp_f32_e32 v166, v166
	v_rcp_f32_e32 v167, v167
	v_add_u32_e32 v158, 0x20, v156
	v_mad_i64_i32 v[158:159], s[18:19], v158, s73, v[152:153]
	v_pk_mul_f32 v[92:93], v[92:93], v[160:161]
	v_pk_mul_f32 v[94:95], v[94:95], v[162:163]
	v_pk_mul_f32 v[84:85], v[84:85], v[164:165]
	v_pk_mul_f32 v[86:87], v[86:87], v[166:167]
	v_pk_mul_f32 v[88:89], v[88:89], v[92:93]
	v_pk_mul_f32 v[90:91], v[90:91], v[94:95]
	v_pk_mul_f32 v[80:81], v[80:81], v[84:85]
	v_pk_mul_f32 v[82:83], v[82:83], v[86:87]
	v_cvt_pk_bf16_f32 v88, v88, v89
	v_cvt_pk_bf16_f32 v89, v90, v91
	v_cvt_pk_bf16_f32 v90, v80, v81
	v_cvt_pk_bf16_f32 v91, v82, v83
	global_store_dwordx4 v[158:159], v[88:91], off sc1
	v_pk_mul_f32 v[160:161], v[76:77], v[168:169]
	v_pk_mul_f32 v[162:163], v[78:79], v[168:169]
	v_pk_mul_f32 v[164:165], v[68:69], v[168:169]
	v_pk_mul_f32 v[166:167], v[70:71], v[168:169]
	v_exp_f32_e32 v160, v160
	v_exp_f32_e32 v161, v161
	v_exp_f32_e32 v162, v162
	v_exp_f32_e32 v163, v163
	v_exp_f32_e32 v164, v164
	v_exp_f32_e32 v165, v165
	v_exp_f32_e32 v166, v166
	v_exp_f32_e32 v167, v167
	v_pk_add_f32 v[160:161], v[160:161], v[170:171]
	v_pk_add_f32 v[162:163], v[162:163], v[170:171]
	v_pk_add_f32 v[164:165], v[164:165], v[170:171]
	v_pk_add_f32 v[166:167], v[166:167], v[170:171]
	v_rcp_f32_e32 v160, v160
	v_rcp_f32_e32 v161, v161
	v_rcp_f32_e32 v162, v162
	v_rcp_f32_e32 v163, v163
	v_rcp_f32_e32 v164, v164
	v_rcp_f32_e32 v165, v165
	v_rcp_f32_e32 v166, v166
	v_rcp_f32_e32 v167, v167
	v_add_u32_e32 v158, 0x30, v156
	v_mad_i64_i32 v[158:159], s[18:19], v158, s73, v[152:153]
	v_pk_mul_f32 v[76:77], v[76:77], v[160:161]
	v_pk_mul_f32 v[78:79], v[78:79], v[162:163]
	v_pk_mul_f32 v[68:69], v[68:69], v[164:165]
	v_pk_mul_f32 v[70:71], v[70:71], v[166:167]
	v_pk_mul_f32 v[72:73], v[72:73], v[76:77]
	v_pk_mul_f32 v[74:75], v[74:75], v[78:79]
	v_pk_mul_f32 v[64:65], v[64:65], v[68:69]
	v_pk_mul_f32 v[66:67], v[66:67], v[70:71]
	v_cvt_pk_bf16_f32 v72, v72, v73
	v_cvt_pk_bf16_f32 v73, v74, v75
	v_cvt_pk_bf16_f32 v74, v64, v65
	v_cvt_pk_bf16_f32 v75, v66, v67
	global_store_dwordx4 v[158:159], v[72:75], off sc1
	v_pk_mul_f32 v[160:161], v[60:61], v[168:169]
	v_pk_mul_f32 v[162:163], v[62:63], v[168:169]
	v_pk_mul_f32 v[164:165], v[52:53], v[168:169]
	v_pk_mul_f32 v[166:167], v[54:55], v[168:169]
	v_exp_f32_e32 v160, v160
	v_exp_f32_e32 v161, v161
	v_exp_f32_e32 v162, v162
	v_exp_f32_e32 v163, v163
	v_exp_f32_e32 v164, v164
	v_exp_f32_e32 v165, v165
	v_exp_f32_e32 v166, v166
	v_exp_f32_e32 v167, v167
	v_pk_add_f32 v[160:161], v[160:161], v[170:171]
	v_pk_add_f32 v[162:163], v[162:163], v[170:171]
	v_pk_add_f32 v[164:165], v[164:165], v[170:171]
	v_pk_add_f32 v[166:167], v[166:167], v[170:171]
	v_rcp_f32_e32 v160, v160
	v_rcp_f32_e32 v161, v161
	v_rcp_f32_e32 v162, v162
	v_rcp_f32_e32 v163, v163
	v_rcp_f32_e32 v164, v164
	v_rcp_f32_e32 v165, v165
	v_rcp_f32_e32 v166, v166
	v_rcp_f32_e32 v167, v167
	v_add_u32_e32 v158, 0x80, v156
	v_mad_i64_i32 v[158:159], s[18:19], v158, s73, v[152:153]
	v_pk_mul_f32 v[60:61], v[60:61], v[160:161]
	v_pk_mul_f32 v[62:63], v[62:63], v[162:163]
	v_pk_mul_f32 v[52:53], v[52:53], v[164:165]
	v_pk_mul_f32 v[54:55], v[54:55], v[166:167]
	v_pk_mul_f32 v[56:57], v[56:57], v[60:61]
	v_pk_mul_f32 v[58:59], v[58:59], v[62:63]
	v_pk_mul_f32 v[48:49], v[48:49], v[52:53]
	v_pk_mul_f32 v[50:51], v[50:51], v[54:55]
	v_cvt_pk_bf16_f32 v56, v56, v57
	v_cvt_pk_bf16_f32 v57, v58, v59
	v_cvt_pk_bf16_f32 v58, v48, v49
	v_cvt_pk_bf16_f32 v59, v50, v51
	global_store_dwordx4 v[158:159], v[56:59], off sc1
	v_pk_mul_f32 v[160:161], v[44:45], v[168:169]
	v_pk_mul_f32 v[162:163], v[46:47], v[168:169]
	v_pk_mul_f32 v[164:165], v[36:37], v[168:169]
	v_pk_mul_f32 v[166:167], v[38:39], v[168:169]
	v_exp_f32_e32 v160, v160
	v_exp_f32_e32 v161, v161
	v_exp_f32_e32 v162, v162
	v_exp_f32_e32 v163, v163
	v_exp_f32_e32 v164, v164
	v_exp_f32_e32 v165, v165
	v_exp_f32_e32 v166, v166
	v_exp_f32_e32 v167, v167
	v_pk_add_f32 v[160:161], v[160:161], v[170:171]
	v_pk_add_f32 v[162:163], v[162:163], v[170:171]
	v_pk_add_f32 v[164:165], v[164:165], v[170:171]
	v_pk_add_f32 v[166:167], v[166:167], v[170:171]
	v_rcp_f32_e32 v160, v160
	v_rcp_f32_e32 v161, v161
	v_rcp_f32_e32 v162, v162
	v_rcp_f32_e32 v163, v163
	v_rcp_f32_e32 v164, v164
	v_rcp_f32_e32 v165, v165
	v_rcp_f32_e32 v166, v166
	v_rcp_f32_e32 v167, v167
	v_add_u32_e32 v158, 0x90, v156
	v_mad_i64_i32 v[158:159], s[18:19], v158, s73, v[152:153]
	v_pk_mul_f32 v[44:45], v[44:45], v[160:161]
	v_pk_mul_f32 v[46:47], v[46:47], v[162:163]
	v_pk_mul_f32 v[36:37], v[36:37], v[164:165]
	v_pk_mul_f32 v[38:39], v[38:39], v[166:167]
	v_pk_mul_f32 v[40:41], v[40:41], v[44:45]
	v_pk_mul_f32 v[42:43], v[42:43], v[46:47]
	v_pk_mul_f32 v[32:33], v[32:33], v[36:37]
	v_pk_mul_f32 v[34:35], v[34:35], v[38:39]
	v_cvt_pk_bf16_f32 v40, v40, v41
	v_cvt_pk_bf16_f32 v41, v42, v43
	v_cvt_pk_bf16_f32 v42, v32, v33
	v_cvt_pk_bf16_f32 v43, v34, v35
	global_store_dwordx4 v[158:159], v[40:43], off sc1
	v_pk_mul_f32 v[160:161], v[28:29], v[168:169]
	v_pk_mul_f32 v[162:163], v[30:31], v[168:169]
	v_pk_mul_f32 v[164:165], v[20:21], v[168:169]
	v_pk_mul_f32 v[166:167], v[22:23], v[168:169]
	v_exp_f32_e32 v160, v160
	v_exp_f32_e32 v161, v161
	v_exp_f32_e32 v162, v162
	v_exp_f32_e32 v163, v163
	v_exp_f32_e32 v164, v164
	v_exp_f32_e32 v165, v165
	v_exp_f32_e32 v166, v166
	v_exp_f32_e32 v167, v167
	v_pk_add_f32 v[160:161], v[160:161], v[170:171]
	v_pk_add_f32 v[162:163], v[162:163], v[170:171]
	v_pk_add_f32 v[164:165], v[164:165], v[170:171]
	v_pk_add_f32 v[166:167], v[166:167], v[170:171]
	v_rcp_f32_e32 v160, v160
	v_rcp_f32_e32 v161, v161
	v_rcp_f32_e32 v162, v162
	v_rcp_f32_e32 v163, v163
	v_rcp_f32_e32 v164, v164
	v_rcp_f32_e32 v165, v165
	v_rcp_f32_e32 v166, v166
	v_rcp_f32_e32 v167, v167
	v_add_u32_e32 v158, 0xa0, v156
	v_mad_i64_i32 v[158:159], s[18:19], v158, s73, v[152:153]
	v_pk_mul_f32 v[28:29], v[28:29], v[160:161]
	v_pk_mul_f32 v[30:31], v[30:31], v[162:163]
	v_pk_mul_f32 v[20:21], v[20:21], v[164:165]
	v_pk_mul_f32 v[22:23], v[22:23], v[166:167]
	v_pk_mul_f32 v[24:25], v[24:25], v[28:29]
	v_pk_mul_f32 v[26:27], v[26:27], v[30:31]
	v_pk_mul_f32 v[16:17], v[16:17], v[20:21]
	v_pk_mul_f32 v[18:19], v[18:19], v[22:23]
	v_cvt_pk_bf16_f32 v24, v24, v25
	v_cvt_pk_bf16_f32 v25, v26, v27
	v_cvt_pk_bf16_f32 v26, v16, v17
	v_cvt_pk_bf16_f32 v27, v18, v19
	global_store_dwordx4 v[158:159], v[24:27], off sc1
	v_pk_mul_f32 v[160:161], v[12:13], v[168:169]
	v_pk_mul_f32 v[162:163], v[14:15], v[168:169]
	v_pk_mul_f32 v[164:165], v[4:5], v[168:169]
	v_pk_mul_f32 v[166:167], v[6:7], v[168:169]
	v_exp_f32_e32 v160, v160
	v_exp_f32_e32 v161, v161
	v_exp_f32_e32 v162, v162
	v_exp_f32_e32 v163, v163
	v_exp_f32_e32 v164, v164
	v_exp_f32_e32 v165, v165
	v_exp_f32_e32 v166, v166
	v_exp_f32_e32 v167, v167
	v_pk_add_f32 v[160:161], v[160:161], v[170:171]
	v_pk_add_f32 v[162:163], v[162:163], v[170:171]
	v_pk_add_f32 v[164:165], v[164:165], v[170:171]
	v_pk_add_f32 v[166:167], v[166:167], v[170:171]
	v_rcp_f32_e32 v160, v160
	v_rcp_f32_e32 v161, v161
	v_rcp_f32_e32 v162, v162
	v_rcp_f32_e32 v163, v163
	v_rcp_f32_e32 v164, v164
	v_rcp_f32_e32 v165, v165
	v_rcp_f32_e32 v166, v166
	v_rcp_f32_e32 v167, v167
	v_add_u32_e32 v158, 0xb0, v156
	v_mad_i64_i32 v[158:159], s[18:19], v158, s73, v[152:153]
	v_pk_mul_f32 v[12:13], v[12:13], v[160:161]
	v_pk_mul_f32 v[14:15], v[14:15], v[162:163]
	v_pk_mul_f32 v[4:5], v[4:5], v[164:165]
	v_pk_mul_f32 v[6:7], v[6:7], v[166:167]
	v_pk_mul_f32 v[8:9], v[8:9], v[12:13]
	v_pk_mul_f32 v[10:11], v[10:11], v[14:15]
	v_pk_mul_f32 v[0:1], v[0:1], v[4:5]
	v_pk_mul_f32 v[2:3], v[2:3], v[6:7]
	v_cvt_pk_bf16_f32 v8, v8, v9
	v_cvt_pk_bf16_f32 v9, v10, v11
	v_cvt_pk_bf16_f32 v10, v0, v1
	v_cvt_pk_bf16_f32 v11, v2, v3
	global_store_dwordx4 v[158:159], v[8:11], off sc1
	s_mov_b64 s[18:19], s[10:11]
	s_cbranch_vccz .LBB0_1101
	s_waitcnt vmcnt(0)
	s_cmpk_gt_u32 s14, 0xff
	s_cbranch_scc1 .LBB0_1108
	s_barrier

.LBB0_1234:
	s_add_i32 s40, s10, 2
	s_add_u32 s12, s8, 0x80
	s_addc_u32 s11, s9, 0
	s_add_i32 s41, 0, 0x10000
	s_cmp_eq_u32 s29, s10
	s_cselect_b32 s10, s2, s12
	s_cselect_b32 s11, s3, s11
	s_cselect_b32 s13, s7, s39
	s_cselect_b32 s12, s6, s38
	s_add_i32 m0, s22, 0xc000
	ds_read_b128 v[172:175], v155
	ds_read_b128 v[180:183], v155 offset:2048
	ds_read_b128 v[188:191], v155 offset:4096
	ds_read_b128 v[220:223], v155 offset:6144
	ds_read_b128 v[176:179], v155 offset:1024
	ds_read_b128 v[184:187], v155 offset:3072
	ds_read_b128 v[216:219], v155 offset:5120
	ds_read_b128 v[224:227], v155 offset:7168
	global_load_lds_dwordx4 v130, s[8:9]
	s_add_i32 m0, s22, 0xe000
	s_nop 0
	global_load_lds_dwordx4 v150, s[8:9]
	s_waitcnt lgkmcnt(8)
	s_waitcnt vmcnt(10)
	s_waitcnt lgkmcnt(4)
	s_barrier
	v_mfma_f32_16x16x32_bf16 v[124:127], v[156:159], v[172:175], v[124:127]
	v_mfma_f32_16x16x32_bf16 v[120:123], v[164:167], v[172:175], v[120:123]
	v_mfma_f32_16x16x32_bf16 v[116:119], v[156:159], v[180:183], v[116:119]
	v_mfma_f32_16x16x32_bf16 v[108:111], v[164:167], v[180:183], v[108:111]
	v_mfma_f32_16x16x32_bf16 v[100:103], v[156:159], v[188:191], v[100:103]
	v_mfma_f32_16x16x32_bf16 v[92:95], v[164:167], v[188:191], v[92:95]
	v_mfma_f32_16x16x32_bf16 v[84:87], v[156:159], v[220:223], v[84:87]
	v_mfma_f32_16x16x32_bf16 v[76:79], v[164:167], v[220:223], v[76:79]
	s_waitcnt lgkmcnt(0)
	v_mfma_f32_16x16x32_bf16 v[124:127], v[160:163], v[176:179], v[124:127]
	v_mfma_f32_16x16x32_bf16 v[120:123], v[168:171], v[176:179], v[120:123]
	v_mfma_f32_16x16x32_bf16 v[116:119], v[160:163], v[184:187], v[116:119]
	v_mfma_f32_16x16x32_bf16 v[108:111], v[168:171], v[184:187], v[108:111]
	v_mfma_f32_16x16x32_bf16 v[100:103], v[160:163], v[216:219], v[100:103]
	v_mfma_f32_16x16x32_bf16 v[92:95], v[168:171], v[216:219], v[92:95]
	v_mfma_f32_16x16x32_bf16 v[84:87], v[160:163], v[224:227], v[84:87]
	v_mfma_f32_16x16x32_bf16 v[76:79], v[168:171], v[224:227], v[76:79]
	s_barrier
	s_add_i32 s42, 0, 0x14000
	v_add_u32_e32 v152, s42, v154
	s_add_i32 s41, s41, s19
	ds_read_b128 v[228:231], v152
	ds_read_b128 v[236:239], v152 offset:2048
	ds_read_b128 v[232:235], v152 offset:1024
	ds_read_b128 v[240:243], v152 offset:3072
	v_lshl_add_u64 v[152:153], s[12:13], 0, v[132:133]
	s_mov_b32 m0, s41
	v_lshl_add_u64 v[244:245], s[12:13], 0, v[128:129]
	global_load_lds_dwordx4 v132, s[12:13]
	s_add_i32 m0, s41, 0x2000
	s_nop 0
	global_load_lds_dwordx4 v128, s[12:13]
	s_waitcnt vmcnt(10)
	s_waitcnt lgkmcnt(2)
	s_barrier
	v_mfma_f32_16x16x32_bf16 v[112:115], v[228:231], v[172:175], v[112:115]
	v_mfma_f32_16x16x32_bf16 v[104:107], v[236:239], v[172:175], v[104:107]
	v_mfma_f32_16x16x32_bf16 v[96:99], v[228:231], v[180:183], v[96:99]
	v_mfma_f32_16x16x32_bf16 v[88:91], v[236:239], v[180:183], v[88:91]
	v_mfma_f32_16x16x32_bf16 v[80:83], v[228:231], v[188:191], v[80:83]
	v_mfma_f32_16x16x32_bf16 v[72:75], v[236:239], v[188:191], v[72:75]
	v_mfma_f32_16x16x32_bf16 v[68:71], v[228:231], v[220:223], v[68:71]
	v_mfma_f32_16x16x32_bf16 v[64:67], v[236:239], v[220:223], v[64:67]
	s_waitcnt lgkmcnt(0)
	v_mfma_f32_16x16x32_bf16 v[112:115], v[232:235], v[176:179], v[112:115]
	v_mfma_f32_16x16x32_bf16 v[104:107], v[240:243], v[176:179], v[104:107]
	v_mfma_f32_16x16x32_bf16 v[96:99], v[232:235], v[184:187], v[96:99]
	v_mfma_f32_16x16x32_bf16 v[88:91], v[240:243], v[184:187], v[88:91]
	v_mfma_f32_16x16x32_bf16 v[80:83], v[232:235], v[216:219], v[80:83]
	v_mfma_f32_16x16x32_bf16 v[72:75], v[240:243], v[216:219], v[72:75]
	v_mfma_f32_16x16x32_bf16 v[68:71], v[232:235], v[224:227], v[68:71]
	v_mfma_f32_16x16x32_bf16 v[64:67], v[240:243], v[224:227], v[64:67]
	s_mov_b32 m0, s22
	v_lshl_add_u64 v[246:247], s[10:11], 0, v[132:133]
	s_barrier
	ds_read_b128 v[172:175], v155 offset:16384
	ds_read_b128 v[180:183], v155 offset:18432
	ds_read_b128 v[188:191], v155 offset:20480
	ds_read_b128 v[220:223], v155 offset:22528
	ds_read_b128 v[176:179], v155 offset:17408
	ds_read_b128 v[184:187], v155 offset:19456
	ds_read_b128 v[216:219], v155 offset:21504
	ds_read_b128 v[224:227], v155 offset:23552
	global_load_lds_dwordx4 v132, s[10:11]
	v_lshl_add_u64 v[248:249], s[10:11], 0, v[128:129]
	s_mov_b32 m0, s23
	s_nop 0
	global_load_lds_dwordx4 v128, s[10:11]
	s_waitcnt vmcnt(10)
	s_waitcnt lgkmcnt(4)
	s_barrier
	v_mfma_f32_16x16x32_bf16 v[60:63], v[156:159], v[172:175], v[60:63]
	v_mfma_f32_16x16x32_bf16 v[56:59], v[164:167], v[172:175], v[56:59]
	v_mfma_f32_16x16x32_bf16 v[52:55], v[156:159], v[180:183], v[52:55]
	v_mfma_f32_16x16x32_bf16 v[44:47], v[164:167], v[180:183], v[44:47]
	v_mfma_f32_16x16x32_bf16 v[36:39], v[156:159], v[188:191], v[36:39]
	v_mfma_f32_16x16x32_bf16 v[28:31], v[164:167], v[188:191], v[28:31]
	v_mfma_f32_16x16x32_bf16 v[20:23], v[156:159], v[220:223], v[20:23]
	v_mfma_f32_16x16x32_bf16 v[12:15], v[164:167], v[220:223], v[12:15]
	s_waitcnt lgkmcnt(0)
	v_mfma_f32_16x16x32_bf16 v[60:63], v[160:163], v[176:179], v[60:63]
	v_mfma_f32_16x16x32_bf16 v[56:59], v[168:171], v[176:179], v[56:59]
	v_mfma_f32_16x16x32_bf16 v[52:55], v[160:163], v[184:187], v[52:55]
	v_mfma_f32_16x16x32_bf16 v[44:47], v[168:171], v[184:187], v[44:47]
	v_mfma_f32_16x16x32_bf16 v[36:39], v[160:163], v[216:219], v[36:39]
	v_mfma_f32_16x16x32_bf16 v[28:31], v[168:171], v[216:219], v[28:31]
	v_mfma_f32_16x16x32_bf16 v[20:23], v[160:163], v[224:227], v[20:23]
	v_mfma_f32_16x16x32_bf16 v[12:15], v[168:171], v[224:227], v[12:15]
	s_barrier
	s_add_u32 s12, s12, s58
	s_addc_u32 s13, s13, 0
	s_add_i32 s41, s42, s19
	v_lshl_add_u64 v[250:251], s[12:13], 0, v[132:133]
	s_mov_b32 m0, s41
	v_lshl_add_u64 v[252:253], s[12:13], 0, v[128:129]
	global_load_lds_dwordx4 v132, s[12:13]
	s_add_i32 m0, s41, 0x2000
	s_nop 0
	global_load_lds_dwordx4 v128, s[12:13]
	v_add_u32_e32 v168, 0x18000, v154
	ds_read_b128 v[156:159], v168
	ds_read_b128 v[160:163], v168 offset:1024
	ds_read_b128 v[164:167], v168 offset:2048
	ds_read_b128 v[168:171], v168 offset:3072
	s_waitcnt vmcnt(10)
	s_barrier
	v_mfma_f32_16x16x32_bf16 v[48:51], v[228:231], v[172:175], v[48:51]
	v_mfma_f32_16x16x32_bf16 v[40:43], v[236:239], v[172:175], v[40:43]
	v_mfma_f32_16x16x32_bf16 v[32:35], v[228:231], v[180:183], v[32:35]
	v_mfma_f32_16x16x32_bf16 v[24:27], v[236:239], v[180:183], v[24:27]
	v_mfma_f32_16x16x32_bf16 v[16:19], v[228:231], v[188:191], v[16:19]
	v_mfma_f32_16x16x32_bf16 v[8:11], v[236:239], v[188:191], v[8:11]
	v_mfma_f32_16x16x32_bf16 v[4:7], v[228:231], v[220:223], v[4:7]
	v_mfma_f32_16x16x32_bf16 v[0:3], v[236:239], v[220:223], v[0:3]
	v_mfma_f32_16x16x32_bf16 v[48:51], v[232:235], v[176:179], v[48:51]
	v_mfma_f32_16x16x32_bf16 v[40:43], v[240:243], v[176:179], v[40:43]
	v_mfma_f32_16x16x32_bf16 v[32:35], v[232:235], v[184:187], v[32:35]
	v_mfma_f32_16x16x32_bf16 v[24:27], v[240:243], v[184:187], v[24:27]
	v_mfma_f32_16x16x32_bf16 v[16:19], v[232:235], v[216:219], v[16:19]
	v_mfma_f32_16x16x32_bf16 v[8:11], v[240:243], v[216:219], v[8:11]
	v_mfma_f32_16x16x32_bf16 v[4:7], v[232:235], v[224:227], v[4:7]
	v_mfma_f32_16x16x32_bf16 v[0:3], v[240:243], v[224:227], v[0:3]
	s_add_i32 s12, 0, 0x18000
	s_barrier
	s_add_u32 s10, s10, s58
	s_addc_u32 s11, s11, 0
	s_mov_b32 m0, s24
	ds_read_b128 v[172:175], v155 offset:32768
	ds_read_b128 v[180:183], v155 offset:34816
	ds_read_b128 v[188:191], v155 offset:36864
	ds_read_b128 v[220:223], v155 offset:38912
	ds_read_b128 v[176:179], v155 offset:33792
	ds_read_b128 v[184:187], v155 offset:35840
	ds_read_b128 v[216:219], v155 offset:37888
	ds_read_b128 v[224:227], v155 offset:39936
	global_load_lds_dwordx4 v132, s[10:11]
	s_mov_b32 m0, s25
	s_nop 0
	global_load_lds_dwordx4 v128, s[10:11]
	s_waitcnt lgkmcnt(8)
	s_waitcnt vmcnt(10)
	s_waitcnt lgkmcnt(4)
	s_barrier
	v_mfma_f32_16x16x32_bf16 v[124:127], v[156:159], v[172:175], v[124:127]
	v_mfma_f32_16x16x32_bf16 v[120:123], v[164:167], v[172:175], v[120:123]
	v_mfma_f32_16x16x32_bf16 v[116:119], v[156:159], v[180:183], v[116:119]
	v_mfma_f32_16x16x32_bf16 v[108:111], v[164:167], v[180:183], v[108:111]
	v_mfma_f32_16x16x32_bf16 v[100:103], v[156:159], v[188:191], v[100:103]
	v_mfma_f32_16x16x32_bf16 v[92:95], v[164:167], v[188:191], v[92:95]
	v_mfma_f32_16x16x32_bf16 v[84:87], v[156:159], v[220:223], v[84:87]
	v_mfma_f32_16x16x32_bf16 v[76:79], v[164:167], v[220:223], v[76:79]
	s_waitcnt lgkmcnt(0)
	v_mfma_f32_16x16x32_bf16 v[124:127], v[160:163], v[176:179], v[124:127]
	v_mfma_f32_16x16x32_bf16 v[120:123], v[168:171], v[176:179], v[120:123]
	v_mfma_f32_16x16x32_bf16 v[116:119], v[160:163], v[184:187], v[116:119]
	v_mfma_f32_16x16x32_bf16 v[108:111], v[168:171], v[184:187], v[108:111]
	v_mfma_f32_16x16x32_bf16 v[100:103], v[160:163], v[216:219], v[100:103]
	v_mfma_f32_16x16x32_bf16 v[92:95], v[168:171], v[216:219], v[92:95]
	v_mfma_f32_16x16x32_bf16 v[84:87], v[160:163], v[224:227], v[84:87]
	v_mfma_f32_16x16x32_bf16 v[76:79], v[168:171], v[224:227], v[76:79]
	s_barrier
	s_add_i32 s10, 0, 0x1c000
	s_add_i32 s11, s12, s19
	v_add_u32_e32 v200, s10, v154
	v_lshl_add_u64 v[152:153], v[152:153], 0, s[66:67]
	s_mov_b32 m0, s11
	ds_read_b128 v[228:231], v200
	ds_read_b128 v[236:239], v200 offset:2048
	ds_read_b128 v[232:235], v200 offset:1024
	ds_read_b128 v[240:243], v200 offset:3072
	global_load_lds_dwordx4 v[152:153], off
	v_lshl_add_u64 v[152:153], v[244:245], 0, s[66:67]
	s_add_i32 m0, s11, 0x2000
	s_nop 0
	global_load_lds_dwordx4 v[152:153], off
	s_waitcnt vmcnt(10)
	s_waitcnt lgkmcnt(2)
	s_barrier
	v_mfma_f32_16x16x32_bf16 v[112:115], v[228:231], v[172:175], v[112:115]
	v_mfma_f32_16x16x32_bf16 v[104:107], v[236:239], v[172:175], v[104:107]
	v_mfma_f32_16x16x32_bf16 v[96:99], v[228:231], v[180:183], v[96:99]
	v_mfma_f32_16x16x32_bf16 v[88:91], v[236:239], v[180:183], v[88:91]
	v_mfma_f32_16x16x32_bf16 v[80:83], v[228:231], v[188:191], v[80:83]
	v_mfma_f32_16x16x32_bf16 v[72:75], v[236:239], v[188:191], v[72:75]
	v_mfma_f32_16x16x32_bf16 v[68:71], v[228:231], v[220:223], v[68:71]
	v_mfma_f32_16x16x32_bf16 v[64:67], v[236:239], v[220:223], v[64:67]
	s_waitcnt lgkmcnt(0)
	v_mfma_f32_16x16x32_bf16 v[112:115], v[232:235], v[176:179], v[112:115]
	v_mfma_f32_16x16x32_bf16 v[104:107], v[240:243], v[176:179], v[104:107]
	v_mfma_f32_16x16x32_bf16 v[96:99], v[232:235], v[184:187], v[96:99]
	v_mfma_f32_16x16x32_bf16 v[88:91], v[240:243], v[184:187], v[88:91]
	v_mfma_f32_16x16x32_bf16 v[80:83], v[232:235], v[216:219], v[80:83]
	v_mfma_f32_16x16x32_bf16 v[72:75], v[240:243], v[216:219], v[72:75]
	v_mfma_f32_16x16x32_bf16 v[68:71], v[232:235], v[224:227], v[68:71]
	v_mfma_f32_16x16x32_bf16 v[64:67], v[240:243], v[224:227], v[64:67]
	s_mov_b32 m0, s26
	v_lshl_add_u64 v[152:153], v[246:247], 0, s[66:67]
	s_barrier
	ds_read_b128 v[172:175], v155 offset:49152
	ds_read_b128 v[180:183], v155 offset:51200
	ds_read_b128 v[188:191], v155 offset:53248
	ds_read_b128 v[220:223], v155 offset:55296
	ds_read_b128 v[176:179], v155 offset:50176
	ds_read_b128 v[184:187], v155 offset:52224
	ds_read_b128 v[216:219], v155 offset:54272
	ds_read_b128 v[224:227], v155 offset:56320
	global_load_lds_dwordx4 v[152:153], off
	v_lshl_add_u64 v[152:153], v[248:249], 0, s[66:67]
	s_mov_b32 m0, s27
	s_nop 0
	global_load_lds_dwordx4 v[152:153], off
	s_waitcnt vmcnt(10)
	s_waitcnt lgkmcnt(4)
	s_barrier
	v_mfma_f32_16x16x32_bf16 v[60:63], v[156:159], v[172:175], v[60:63]
	v_mfma_f32_16x16x32_bf16 v[56:59], v[164:167], v[172:175], v[56:59]
	v_mfma_f32_16x16x32_bf16 v[52:55], v[156:159], v[180:183], v[52:55]
	v_mfma_f32_16x16x32_bf16 v[44:47], v[164:167], v[180:183], v[44:47]
	v_mfma_f32_16x16x32_bf16 v[36:39], v[156:159], v[188:191], v[36:39]
	v_mfma_f32_16x16x32_bf16 v[28:31], v[164:167], v[188:191], v[28:31]
	v_mfma_f32_16x16x32_bf16 v[20:23], v[156:159], v[220:223], v[20:23]
	v_mfma_f32_16x16x32_bf16 v[12:15], v[164:167], v[220:223], v[12:15]
	s_waitcnt lgkmcnt(0)
	v_mfma_f32_16x16x32_bf16 v[60:63], v[160:163], v[176:179], v[60:63]
	v_mfma_f32_16x16x32_bf16 v[56:59], v[168:171], v[176:179], v[56:59]
	v_mfma_f32_16x16x32_bf16 v[52:55], v[160:163], v[184:187], v[52:55]
	v_mfma_f32_16x16x32_bf16 v[44:47], v[168:171], v[184:187], v[44:47]
	v_mfma_f32_16x16x32_bf16 v[36:39], v[160:163], v[216:219], v[36:39]
	v_mfma_f32_16x16x32_bf16 v[28:31], v[168:171], v[216:219], v[28:31]
	v_mfma_f32_16x16x32_bf16 v[20:23], v[160:163], v[224:227], v[20:23]
	v_mfma_f32_16x16x32_bf16 v[12:15], v[168:171], v[224:227], v[12:15]
	s_barrier
	s_add_i32 s10, s10, s19
	v_lshl_add_u64 v[152:153], v[250:251], 0, s[66:67]
	s_mov_b32 m0, s10
	s_nop 0
	global_load_lds_dwordx4 v[152:153], off
	v_lshl_add_u64 v[152:153], v[252:253], 0, s[66:67]
	s_add_i32 m0, s10, 0x2000
	s_nop 0
	global_load_lds_dwordx4 v[152:153], off
	v_add_u32_e32 v168, 0x10000, v154
	ds_read_b128 v[156:159], v168
	ds_read_b128 v[160:163], v168 offset:1024
	ds_read_b128 v[164:167], v168 offset:2048
	ds_read_b128 v[168:171], v168 offset:3072
	s_waitcnt vmcnt(10)
	s_barrier
	v_mfma_f32_16x16x32_bf16 v[48:51], v[228:231], v[172:175], v[48:51]
	v_mfma_f32_16x16x32_bf16 v[40:43], v[236:239], v[172:175], v[40:43]
	v_mfma_f32_16x16x32_bf16 v[32:35], v[228:231], v[180:183], v[32:35]
	v_mfma_f32_16x16x32_bf16 v[24:27], v[236:239], v[180:183], v[24:27]
	v_mfma_f32_16x16x32_bf16 v[16:19], v[228:231], v[188:191], v[16:19]
	v_mfma_f32_16x16x32_bf16 v[8:11], v[236:239], v[188:191], v[8:11]
	v_mfma_f32_16x16x32_bf16 v[4:7], v[228:231], v[220:223], v[4:7]
	v_mfma_f32_16x16x32_bf16 v[0:3], v[236:239], v[220:223], v[0:3]
	v_mfma_f32_16x16x32_bf16 v[48:51], v[232:235], v[176:179], v[48:51]
	v_mfma_f32_16x16x32_bf16 v[40:43], v[240:243], v[176:179], v[40:43]
	v_mfma_f32_16x16x32_bf16 v[32:35], v[232:235], v[184:187], v[32:35]
	v_mfma_f32_16x16x32_bf16 v[24:27], v[240:243], v[184:187], v[24:27]
	v_mfma_f32_16x16x32_bf16 v[16:19], v[232:235], v[216:219], v[16:19]
	v_mfma_f32_16x16x32_bf16 v[8:11], v[240:243], v[216:219], v[8:11]
	v_mfma_f32_16x16x32_bf16 v[4:7], v[232:235], v[224:227], v[4:7]
	v_mfma_f32_16x16x32_bf16 v[0:3], v[240:243], v[224:227], v[0:3]
	s_add_u32 s8, s8, 0x100
	s_addc_u32 s9, s9, 0
	s_add_u32 s38, s38, 0x100
	s_addc_u32 s39, s39, 0
	s_cmp_ge_u32 s40, s28
	s_mov_b32 s10, s40
	s_barrier
	s_cbranch_scc0 .LBB0_1234
	s_waitcnt lgkmcnt(0)
	v_mov_b32_e32 v152, v135
	s_mov_b64 s[8:9], s[0:1]
	v_readfirstlane_b32 s10, v152
	s_ashr_i32 s12, s10, 2
	s_load_dwordx2 s[8:9], s[8:9], 0x88
	s_lshl_b32 s11, s36, 8
	s_andn2_b32 s12, s12, 63
	s_lshr_b32 s10, s10, 1
	s_add_i32 s12, s12, s11
	s_lshl_b32 s11, s37, 8
	s_and_b32 s10, s10, 0x60
	v_and_or_b32 v156, v152, 15, s12
	s_or_b32 s10, s10, s11
	v_lshrrev_b32_e32 v152, 1, v152
	v_and_or_b32 v152, v152, 24, s10
	v_ashrrev_i32_e32 v153, 31, v152
	s_waitcnt lgkmcnt(0)
	v_lshl_add_u64 v[152:153], v[152:153], 1, s[8:9]
	s_mov_b64 s[8:9], 0x62a4400
	v_ashrrev_i32_e32 v157, 31, v156
	v_lshl_add_u64 v[158:159], v[152:153], 0, s[8:9]
	v_lshlrev_b64 v[152:153], 11, v[156:157]
	v_lshl_add_u64 v[152:153], v[158:159], 0, v[152:153]
	s_mov_b64 s[8:9], 0x40000
	v_cvt_pk_bf16_f32 v68, v68, v69
	v_cvt_pk_bf16_f32 v69, v70, v71
	v_cvt_pk_bf16_f32 v70, v64, v65
	v_lshl_add_u64 v[64:65], v[152:153], 0, s[8:9]
	s_mov_b32 s8, 0x40000
	v_cvt_pk_bf16_f32 v60, v60, v61
	v_cvt_pk_bf16_f32 v61, v62, v63
	v_cvt_pk_bf16_f32 v62, v56, v57
	v_add_co_u32_e32 v56, vcc, s8, v152
	v_cvt_pk_bf16_f32 v48, v48, v49
	v_cvt_pk_bf16_f32 v49, v50, v51
	s_mov_b64 s[8:9], 0x48000
	s_nop 0
	v_addc_co_u32_e32 v57, vcc, 0, v153, vcc
	v_cvt_pk_bf16_f32 v50, v40, v41
	v_cvt_pk_bf16_f32 v51, v42, v43
	global_store_dwordx4 v[64:65], v[48:51], off offset:256 sc1
	v_cvt_pk_bf16_f32 v42, v44, v45
	v_cvt_pk_bf16_f32 v32, v32, v33
	v_cvt_pk_bf16_f32 v33, v34, v35
	v_cvt_pk_bf16_f32 v112, v112, v113
	v_cvt_pk_bf16_f32 v113, v114, v115
	s_nop 1
	v_lshl_add_u64 v[48:49], v[152:153], 0, s[8:9]
	s_mov_b32 s8, 0x48000
	v_add_co_u32_e32 v44, vcc, s8, v152
	s_mov_b64 s[8:9], 0x50000
	v_cvt_pk_bf16_f32 v114, v104, v105
	v_or_b32_e32 v104, 16, v156
	v_addc_co_u32_e32 v45, vcc, 0, v153, vcc
	v_cvt_pk_bf16_f32 v34, v24, v25
	v_cvt_pk_bf16_f32 v35, v26, v27
	global_store_dwordx4 v[48:49], v[32:35], off offset:256 sc1
	v_ashrrev_i32_e32 v105, 31, v104
	v_cvt_pk_bf16_f32 v96, v96, v97
	v_cvt_pk_bf16_f32 v97, v98, v99
	v_cvt_pk_bf16_f32 v98, v88, v89
	v_or_b32_e32 v88, 32, v156
	v_lshl_add_u64 v[32:33], v[152:153], 0, s[8:9]
	s_mov_b32 s8, 0x50000
	v_cvt_pk_bf16_f32 v26, v28, v29
	v_add_co_u32_e32 v28, vcc, s8, v152
	v_cvt_pk_bf16_f32 v16, v16, v17
	v_cvt_pk_bf16_f32 v17, v18, v19
	s_mov_b64 s[8:9], 0x58000
	v_lshlrev_b64 v[104:105], 11, v[104:105]
	v_ashrrev_i32_e32 v89, 31, v88
	v_cvt_pk_bf16_f32 v80, v80, v81
	v_cvt_pk_bf16_f32 v81, v82, v83
	v_cvt_pk_bf16_f32 v82, v72, v73
	v_or_b32_e32 v72, 48, v156
	v_addc_co_u32_e32 v29, vcc, 0, v153, vcc
	v_cvt_pk_bf16_f32 v18, v8, v9
	v_cvt_pk_bf16_f32 v19, v10, v11
	global_store_dwordx4 v[32:33], v[16:19], off offset:256 sc1
	v_cvt_pk_bf16_f32 v115, v106, v107
	global_store_dwordx4 v[152:153], v[112:115], off offset:256 sc1
	v_lshlrev_b64 v[88:89], 11, v[88:89]
	v_lshl_add_u64 v[16:17], v[152:153], 0, s[8:9]
	s_mov_b32 s8, 0x58000
	v_lshl_add_u64 v[112:113], v[158:159], 0, v[104:105]
	v_ashrrev_i32_e32 v73, 31, v72
	v_cvt_pk_bf16_f32 v10, v12, v13
	v_add_co_u32_e32 v12, vcc, s8, v152
	v_cvt_pk_bf16_f32 v99, v90, v91
	global_store_dwordx4 v[112:113], v[96:99], off offset:256 sc1
	v_lshlrev_b64 v[72:73], 11, v[72:73]
	v_addc_co_u32_e32 v13, vcc, 0, v153, vcc
	v_lshl_add_u64 v[96:97], v[158:159], 0, v[88:89]
	v_cvt_pk_bf16_f32 v83, v74, v75
	global_store_dwordx4 v[96:97], v[80:83], off offset:256 sc1
	s_and_b64 vcc, exec, s[4:5]
	s_mov_b32 s37, s34
	v_lshl_add_u64 v[80:81], v[158:159], 0, v[72:73]
	s_mov_b32 s36, s35
	s_mov_b64 s[10:11], s[6:7]
	s_mov_b64 s[12:13], s[2:3]
	v_cvt_pk_bf16_f32 v124, v124, v125
	v_cvt_pk_bf16_f32 v125, v126, v127
	v_cvt_pk_bf16_f32 v126, v120, v121
	v_cvt_pk_bf16_f32 v127, v122, v123
	global_store_dwordx4 v[152:153], v[124:127], off sc1
	v_cvt_pk_bf16_f32 v104, v116, v117
	v_cvt_pk_bf16_f32 v105, v118, v119
	v_cvt_pk_bf16_f32 v106, v108, v109
	v_cvt_pk_bf16_f32 v107, v110, v111
	global_store_dwordx4 v[112:113], v[104:107], off sc1
	v_cvt_pk_bf16_f32 v88, v100, v101
	v_cvt_pk_bf16_f32 v89, v102, v103
	v_cvt_pk_bf16_f32 v90, v92, v93
	v_cvt_pk_bf16_f32 v91, v94, v95
	global_store_dwordx4 v[96:97], v[88:91], off sc1
	v_cvt_pk_bf16_f32 v72, v84, v85
	v_cvt_pk_bf16_f32 v73, v86, v87
	v_cvt_pk_bf16_f32 v74, v76, v77
	v_cvt_pk_bf16_f32 v75, v78, v79
	global_store_dwordx4 v[80:81], v[72:75], off sc1
	v_cvt_pk_bf16_f32 v71, v66, v67
	global_store_dwordx4 v[80:81], v[68:71], off offset:256 sc1
	v_cvt_pk_bf16_f32 v63, v58, v59
	global_store_dwordx4 v[56:57], v[60:63], off sc1
	v_cvt_pk_bf16_f32 v40, v52, v53
	v_cvt_pk_bf16_f32 v41, v54, v55
	v_cvt_pk_bf16_f32 v43, v46, v47
	global_store_dwordx4 v[44:45], v[40:43], off sc1
	v_cvt_pk_bf16_f32 v24, v36, v37
	v_cvt_pk_bf16_f32 v25, v38, v39
	v_cvt_pk_bf16_f32 v27, v30, v31
	global_store_dwordx4 v[28:29], v[24:27], off sc1
	v_cvt_pk_bf16_f32 v8, v20, v21
	v_cvt_pk_bf16_f32 v9, v22, v23
	v_cvt_pk_bf16_f32 v11, v14, v15
	global_store_dwordx4 v[12:13], v[8:11], off sc1
	v_cvt_pk_bf16_f32 v4, v4, v5
	v_cvt_pk_bf16_f32 v5, v6, v7
	v_cvt_pk_bf16_f32 v6, v0, v1
	v_cvt_pk_bf16_f32 v7, v2, v3
	global_store_dwordx4 v[16:17], v[4:7], off offset:256 sc1
	s_cbranch_vccz .LBB0_1223
	s_waitcnt vmcnt(0)
	s_cmpk_gt_u32 s14, 0xff
	s_cbranch_scc1 .LBB0_1238
	s_barrier
